# k21 plus GEMM loop-top segment reordered: all 16 LDS fragment reads issued first, next-address SALU and DMA setup after them
# speedup vs baseline: 1.0073x; 1.0008x over previous
; #define PG8_STAGE(bufoff, gbase, voff) do { _Pragma("unroll") for (int _i = 0; _i < 2; ++_i) \
;         __builtin_amdgcn_global_load_lds((const unsigned*)((const char*)(gbase) + (voff)[_i]), (PG8_LAS unsigned*)(lds + (bufoff) + ldsw + _i * 8192), 16, 0, 0); } while (0)
; #define PG8_LDA(dst, b, h) do { _Pragma("unroll") for (int m = 0; m < 4; ++m) _Pragma("unroll") for (int k = 0; k < 2; ++k) dst[m][k] = *(const PG8_LAS bf16x8*)(lds + PG8_SA(b, h) + aoff + m * 2048 + k * 1024); } while (0)
; #define PG8_LDB(dst, b, h) do { _Pragma("unroll") for (int n = 0; n < 2; ++n) _Pragma("unroll") for (int k = 0; k < 2; ++k) dst[n][k] = *(const PG8_LAS bf16x8*)(lds + PG8_SB(b, h) + boff + n * 2048 + k * 1024); } while (0)
; #define PG8_MMA(ai, bj, At, Bt) do { __builtin_amdgcn_s_setprio(1); _Pragma("unroll") for (int m = 0; m < 4; ++m) _Pragma("unroll") for (int n = 0; n < 2; ++n) _Pragma("unroll") for (int k = 0; k < 2; ++k) \
;         acc[ai][bj][m][n] = __builtin_amdgcn_mfma_f32_16x16x32_bf16(Bt[n][k], At[m][k], acc[ai][bj][m][n], 0, 0, 0); __builtin_amdgcn_s_setprio(0); } while (0)
; #define PG8_WAIT_V(n) asm volatile("s_waitcnt vmcnt(" #n ")" ::: "memory")
; #define PG8_WAIT_L(n) asm volatile("s_waitcnt lgkmcnt(" #n ")" ::: "memory")
; #define PG8_BAR __builtin_amdgcn_s_barrier()
; template <class Epi, class Sched, bool ALIGN_EPI = false, bool SP2 = false>
; __device__ __forceinline__ void gemm_phase(PG8_LAS unsigned char* lds, const Gemm g, const Sched& S, const Epi& E, const int wv0) {
;     ...
;             const bool last = (t == nt - 2);
;             const char* a1 = cA + (size_t)(t + 1) * kstep;
;             const char* a2 = last ? nA : cA + (size_t)(t + 2) * kstep; const char* b2 = last ? nB : cB + (size_t)(t + 2) * kstep;
;             const char* a3 = a2 + kstep; const char* b3 = b2 + kstep;
;             if constexpr (SP2) {
;             PG8_LDB(B0, 0, 0); PG8_LDB(B1, 0, 1); PG8_SCHED; PG8_LDA(At, 0, 0); PG8_STAGE(PG8_SA(1, 1), a1 + hstepA, voffA);
;             PG8_WAIT_V(8); PG8_WAIT_L(0); PG8_BAR; PG8_MMA(0, 0, At, B0); PG8_MMA(0, 1, At, B1); PG8_BAR; PG8_SCHED;
;             PG8_LDA(At, 0, 1); PG8_STAGE(PG8_SB(0, 0), b2, voffB); PG8_STAGE(PG8_SB(0, 1), b2 + hstepB, voffB); PG8_STAGE(PG8_SA(0, 0), a2, voffA);
;             PG8_WAIT_V(8); PG8_WAIT_L(0); PG8_BAR; PG8_MMA(1, 0, At, B0); PG8_MMA(1, 1, At, B1); PG8_BAR; PG8_SCHED;
.LBB0_82:
	ds_read_b128 v[156:159], v152
	ds_read_b128 v[160:163], v152 offset:1024
	ds_read_b128 v[164:167], v152 offset:2048
	ds_read_b128 v[168:171], v152 offset:3072
	ds_read_b128 v[172:175], v153
	ds_read_b128 v[176:179], v153 offset:1024
	ds_read_b128 v[180:183], v153 offset:2048
	ds_read_b128 v[184:187], v153 offset:3072
	ds_read_b128 v[188:191], v154
	ds_read_b128 v[192:195], v154 offset:1024
	ds_read_b128 v[196:199], v154 offset:2048
	ds_read_b128 v[200:203], v154 offset:3072
	ds_read_b128 v[206:209], v154 offset:4096
	ds_read_b128 v[210:213], v154 offset:5120
	ds_read_b128 v[214:217], v154 offset:6144
	ds_read_b128 v[218:221], v154 offset:7168
	s_add_u32 s34, s30, 0xfff80080
	s_addc_u32 s35, s31, -1
	s_cmp_eq_u32 s38, 28
	s_cselect_b32 s37, s25, s35
	s_cselect_b32 s36, s24, s34
	s_cselect_b32 s35, s27, s23
	s_cselect_b32 s34, s26, s21
	s_add_i32 m0, s29, 0xc000
	v_lshl_add_u64 v[146:147], s[30:31], 0, v[140:141]
	global_load_lds_dwordx4 v[146:147], off
	v_lshl_add_u64 v[146:147], s[30:31], 0, v[138:139]
	s_add_i32 m0, s29, 0xe000
	s_nop 0
	global_load_lds_dwordx4 v[146:147], off
	s_waitcnt vmcnt(8)
	s_waitcnt lgkmcnt(0)
	s_barrier
	v_mfma_f32_16x16x32_bf16 v[124:127], v[156:159], v[188:191], v[124:127]
	v_mfma_f32_16x16x32_bf16 v[120:123], v[164:167], v[188:191], v[120:123]
	v_mfma_f32_16x16x32_bf16 v[116:119], v[156:159], v[196:199], v[116:119]
	v_mfma_f32_16x16x32_bf16 v[108:111], v[164:167], v[196:199], v[108:111]
	v_mfma_f32_16x16x32_bf16 v[100:103], v[156:159], v[206:209], v[100:103]
	v_mfma_f32_16x16x32_bf16 v[92:95], v[164:167], v[206:209], v[92:95]
	v_mfma_f32_16x16x32_bf16 v[84:87], v[156:159], v[214:217], v[84:87]
	v_mfma_f32_16x16x32_bf16 v[76:79], v[164:167], v[214:217], v[76:79]
	v_mfma_f32_16x16x32_bf16 v[124:127], v[160:163], v[192:195], v[124:127]
	v_mfma_f32_16x16x32_bf16 v[120:123], v[168:171], v[192:195], v[120:123]
	v_mfma_f32_16x16x32_bf16 v[116:119], v[160:163], v[200:203], v[116:119]
	v_mfma_f32_16x16x32_bf16 v[108:111], v[168:171], v[200:203], v[108:111]
	v_mfma_f32_16x16x32_bf16 v[100:103], v[160:163], v[210:213], v[100:103]
	v_mfma_f32_16x16x32_bf16 v[92:95], v[168:171], v[210:213], v[92:95]
	v_mfma_f32_16x16x32_bf16 v[84:87], v[160:163], v[218:221], v[84:87]
	v_mfma_f32_16x16x32_bf16 v[76:79], v[168:171], v[218:221], v[76:79]
	v_mfma_f32_16x16x32_bf16 v[112:115], v[172:175], v[188:191], v[112:115]
	v_mfma_f32_16x16x32_bf16 v[104:107], v[180:183], v[188:191], v[104:107]
	v_mfma_f32_16x16x32_bf16 v[96:99], v[172:175], v[196:199], v[96:99]
	v_mfma_f32_16x16x32_bf16 v[88:91], v[180:183], v[196:199], v[88:91]
	v_mfma_f32_16x16x32_bf16 v[80:83], v[172:175], v[206:209], v[80:83]
	v_mfma_f32_16x16x32_bf16 v[72:75], v[180:183], v[206:209], v[72:75]
	v_mfma_f32_16x16x32_bf16 v[68:71], v[172:175], v[214:217], v[68:71]
	v_mfma_f32_16x16x32_bf16 v[64:67], v[180:183], v[214:217], v[64:67]
	v_mfma_f32_16x16x32_bf16 v[112:115], v[176:179], v[192:195], v[112:115]
	v_mfma_f32_16x16x32_bf16 v[104:107], v[184:187], v[192:195], v[104:107]
	v_mfma_f32_16x16x32_bf16 v[96:99], v[176:179], v[200:203], v[96:99]
	v_mfma_f32_16x16x32_bf16 v[88:91], v[184:187], v[200:203], v[88:91]
	v_mfma_f32_16x16x32_bf16 v[80:83], v[176:179], v[210:213], v[80:83]
	v_mfma_f32_16x16x32_bf16 v[72:75], v[184:187], v[210:213], v[72:75]
	v_mfma_f32_16x16x32_bf16 v[68:71], v[176:179], v[218:221], v[68:71]
	v_mfma_f32_16x16x32_bf16 v[64:67], v[184:187], v[218:221], v[64:67]
	s_barrier
	ds_read_b128 v[188:191], v154 offset:16384
	ds_read_b128 v[192:195], v154 offset:17408
	ds_read_b128 v[196:199], v154 offset:18432
	ds_read_b128 v[200:203], v154 offset:19456
	ds_read_b128 v[206:209], v154 offset:20480
	ds_read_b128 v[210:213], v154 offset:21504
	ds_read_b128 v[214:217], v154 offset:22528
	ds_read_b128 v[218:221], v154 offset:23552
	s_add_i32 s39, s62, s47
	s_mov_b32 m0, s39
	v_lshl_add_u64 v[146:147], s[34:35], 0, v[132:133]
	global_load_lds_dwordx4 v[146:147], off
	s_add_i32 m0, s39, 0x2000
	s_add_u32 s68, s34, 0x80000
	v_lshl_add_u64 v[222:223], s[34:35], 0, v[128:129]
	s_addc_u32 s69, s35, 0
	s_add_i32 s39, s63, s47
	global_load_lds_dwordx4 v[222:223], off
	v_lshl_add_u64 v[224:225], s[68:69], 0, v[132:133]
	s_mov_b32 m0, s39
	v_lshl_add_u64 v[226:227], s[36:37], 0, v[130:131]
	global_load_lds_dwordx4 v[224:225], off
	v_lshl_add_u64 v[224:225], s[68:69], 0, v[128:129]
	s_add_i32 m0, s39, 0x2000
	s_nop 0
	global_load_lds_dwordx4 v[224:225], off
	v_lshl_add_u64 v[224:225], s[36:37], 0, v[134:135]
	s_mov_b32 m0, s29
	s_nop 0
	global_load_lds_dwordx4 v[224:225], off
	s_mov_b32 m0, s49
	s_nop 0
	global_load_lds_dwordx4 v[226:227], off
	s_waitcnt vmcnt(8)
	s_waitcnt lgkmcnt(0)
	s_barrier
; #define PG8_STAGE(bufoff, gbase, voff) do { _Pragma("unroll") for (int _i = 0; _i < 2; ++_i) \
;         __builtin_amdgcn_global_load_lds((const unsigned*)((const char*)(gbase) + (voff)[_i]), (PG8_LAS unsigned*)(lds + (bufoff) + ldsw + _i * 8192), 16, 0, 0); } while (0)
; #define PG8_LDA(dst, b, h) do { _Pragma("unroll") for (int m = 0; m < 4; ++m) _Pragma("unroll") for (int k = 0; k < 2; ++k) dst[m][k] = *(const PG8_LAS bf16x8*)(lds + PG8_SA(b, h) + aoff + m * 2048 + k * 1024); } while (0)
; #define PG8_LDB(dst, b, h) do { _Pragma("unroll") for (int n = 0; n < 2; ++n) _Pragma("unroll") for (int k = 0; k < 2; ++k) dst[n][k] = *(const PG8_LAS bf16x8*)(lds + PG8_SB(b, h) + boff + n * 2048 + k * 1024); } while (0)
; #define PG8_MMA(ai, bj, At, Bt) do { __builtin_amdgcn_s_setprio(1); _Pragma("unroll") for (int m = 0; m < 4; ++m) _Pragma("unroll") for (int n = 0; n < 2; ++n) _Pragma("unroll") for (int k = 0; k < 2; ++k) \
;         acc[ai][bj][m][n] = __builtin_amdgcn_mfma_f32_16x16x32_bf16(Bt[n][k], At[m][k], acc[ai][bj][m][n], 0, 0, 0); __builtin_amdgcn_s_setprio(0); } while (0)
; #define PG8_WAIT_V(n) asm volatile("s_waitcnt vmcnt(" #n ")" ::: "memory")
; #define PG8_WAIT_L(n) asm volatile("s_waitcnt lgkmcnt(" #n ")" ::: "memory")
; #define PG8_BAR __builtin_amdgcn_s_barrier()
; #define PG8_SCHED __builtin_amdgcn_sched_barrier(0)
; template <class Epi, class Sched, bool ALIGN_EPI = false, bool SP2 = false>
; __device__ __forceinline__ void gemm_phase(PG8_LAS unsigned char* lds, const Gemm g, const Sched& S, const Epi& E, const int wv0) {
;     ...
;             PG8_WAIT_V(8); PG8_WAIT_L(0); PG8_BAR; PG8_MMA(1, 0, At, B0); PG8_MMA(1, 1, At, B1); PG8_BAR; PG8_SCHED;
;             PG8_LDB(B0, 1, 0); PG8_LDB(B1, 1, 1); PG8_SCHED; PG8_LDA(At, 1, 0); PG8_STAGE(PG8_SA(0, 1), a2 + hstepA, voffA);
;             PG8_WAIT_V(8); PG8_WAIT_L(0); PG8_BAR; PG8_MMA(0, 0, At, B0); PG8_MMA(0, 1, At, B1); PG8_BAR; PG8_SCHED;
	v_mfma_f32_16x16x32_bf16 v[60:63], v[156:159], v[188:191], v[60:63]
	v_mfma_f32_16x16x32_bf16 v[56:59], v[164:167], v[188:191], v[56:59]
	v_mfma_f32_16x16x32_bf16 v[52:55], v[156:159], v[196:199], v[52:55]
	v_mfma_f32_16x16x32_bf16 v[44:47], v[164:167], v[196:199], v[44:47]
	v_mfma_f32_16x16x32_bf16 v[36:39], v[156:159], v[206:209], v[36:39]
	v_mfma_f32_16x16x32_bf16 v[28:31], v[164:167], v[206:209], v[28:31]
	v_mfma_f32_16x16x32_bf16 v[20:23], v[156:159], v[214:217], v[20:23]
	v_mfma_f32_16x16x32_bf16 v[12:15], v[164:167], v[214:217], v[12:15]
	v_mfma_f32_16x16x32_bf16 v[60:63], v[160:163], v[192:195], v[60:63]
	v_mfma_f32_16x16x32_bf16 v[56:59], v[168:171], v[192:195], v[56:59]
	v_mfma_f32_16x16x32_bf16 v[52:55], v[160:163], v[200:203], v[52:55]
	v_mfma_f32_16x16x32_bf16 v[44:47], v[168:171], v[200:203], v[44:47]
	v_mfma_f32_16x16x32_bf16 v[36:39], v[160:163], v[210:213], v[36:39]
	v_mfma_f32_16x16x32_bf16 v[28:31], v[168:171], v[210:213], v[28:31]
	v_mfma_f32_16x16x32_bf16 v[20:23], v[160:163], v[218:221], v[20:23]
	v_mfma_f32_16x16x32_bf16 v[12:15], v[168:171], v[218:221], v[12:15]
	v_mfma_f32_16x16x32_bf16 v[48:51], v[172:175], v[188:191], v[48:51]
	v_mfma_f32_16x16x32_bf16 v[40:43], v[180:183], v[188:191], v[40:43]
	v_mfma_f32_16x16x32_bf16 v[32:35], v[172:175], v[196:199], v[32:35]
	v_mfma_f32_16x16x32_bf16 v[24:27], v[180:183], v[196:199], v[24:27]
	v_mfma_f32_16x16x32_bf16 v[16:19], v[172:175], v[206:209], v[16:19]
	v_mfma_f32_16x16x32_bf16 v[8:11], v[180:183], v[206:209], v[8:11]
	v_mfma_f32_16x16x32_bf16 v[4:7], v[172:175], v[214:217], v[4:7]
	v_mfma_f32_16x16x32_bf16 v[0:3], v[180:183], v[214:217], v[0:3]
	v_mfma_f32_16x16x32_bf16 v[48:51], v[176:179], v[192:195], v[48:51]
	v_mfma_f32_16x16x32_bf16 v[40:43], v[184:187], v[192:195], v[40:43]
	v_mfma_f32_16x16x32_bf16 v[32:35], v[176:179], v[200:203], v[32:35]
	v_mfma_f32_16x16x32_bf16 v[24:27], v[184:187], v[200:203], v[24:27]
	v_mfma_f32_16x16x32_bf16 v[16:19], v[176:179], v[210:213], v[16:19]
	v_mfma_f32_16x16x32_bf16 v[8:11], v[184:187], v[210:213], v[8:11]
	v_mfma_f32_16x16x32_bf16 v[4:7], v[176:179], v[218:221], v[4:7]
	v_mfma_f32_16x16x32_bf16 v[0:3], v[184:187], v[218:221], v[0:3]
	s_barrier
	s_add_i32 s39, 0, 0x18000
	v_add_u32_e32 v155, s39, v150
	s_add_i32 s68, 0, 0x1c000
	ds_read_b128 v[156:159], v155
	ds_read_b128 v[160:163], v155 offset:1024
	ds_read_b128 v[164:167], v155 offset:2048
	ds_read_b128 v[168:171], v155 offset:3072
	v_add_u32_e32 v155, s68, v150
	ds_read_b128 v[172:175], v155
	ds_read_b128 v[176:179], v155 offset:1024
	ds_read_b128 v[180:183], v155 offset:2048
	ds_read_b128 v[184:187], v155 offset:3072
	s_add_u32 s36, s36, 0x80000
	s_addc_u32 s37, s37, 0
	s_mov_b32 m0, s50
	v_lshl_add_u64 v[228:229], s[36:37], 0, v[134:135]
	ds_read_b128 v[188:191], v154 offset:32768
	ds_read_b128 v[192:195], v154 offset:33792
	ds_read_b128 v[196:199], v154 offset:34816
	ds_read_b128 v[200:203], v154 offset:35840
	ds_read_b128 v[206:209], v154 offset:36864
	ds_read_b128 v[210:213], v154 offset:37888
	ds_read_b128 v[214:217], v154 offset:38912
	ds_read_b128 v[218:221], v154 offset:39936
	global_load_lds_dwordx4 v[228:229], off
	v_lshl_add_u64 v[228:229], s[36:37], 0, v[130:131]
	s_mov_b32 m0, s51
	s_nop 0
	global_load_lds_dwordx4 v[228:229], off
	s_waitcnt vmcnt(8)
	s_waitcnt lgkmcnt(0)
	s_barrier
	v_mfma_f32_16x16x32_bf16 v[124:127], v[156:159], v[188:191], v[124:127]
	v_mfma_f32_16x16x32_bf16 v[120:123], v[164:167], v[188:191], v[120:123]
	v_mfma_f32_16x16x32_bf16 v[116:119], v[156:159], v[196:199], v[116:119]
	v_mfma_f32_16x16x32_bf16 v[108:111], v[164:167], v[196:199], v[108:111]
	v_mfma_f32_16x16x32_bf16 v[100:103], v[156:159], v[206:209], v[100:103]
	v_mfma_f32_16x16x32_bf16 v[92:95], v[164:167], v[206:209], v[92:95]
	v_mfma_f32_16x16x32_bf16 v[84:87], v[156:159], v[214:217], v[84:87]
	v_mfma_f32_16x16x32_bf16 v[76:79], v[164:167], v[214:217], v[76:79]
	v_mfma_f32_16x16x32_bf16 v[124:127], v[160:163], v[192:195], v[124:127]
	v_mfma_f32_16x16x32_bf16 v[120:123], v[168:171], v[192:195], v[120:123]
	v_mfma_f32_16x16x32_bf16 v[116:119], v[160:163], v[200:203], v[116:119]
	v_mfma_f32_16x16x32_bf16 v[108:111], v[168:171], v[200:203], v[108:111]
	v_mfma_f32_16x16x32_bf16 v[100:103], v[160:163], v[210:213], v[100:103]
	v_mfma_f32_16x16x32_bf16 v[92:95], v[168:171], v[210:213], v[92:95]
	v_mfma_f32_16x16x32_bf16 v[84:87], v[160:163], v[218:221], v[84:87]
	v_mfma_f32_16x16x32_bf16 v[76:79], v[168:171], v[218:221], v[76:79]
	v_mfma_f32_16x16x32_bf16 v[112:115], v[172:175], v[188:191], v[112:115]
	v_mfma_f32_16x16x32_bf16 v[104:107], v[180:183], v[188:191], v[104:107]
	v_mfma_f32_16x16x32_bf16 v[96:99], v[172:175], v[196:199], v[96:99]
	v_mfma_f32_16x16x32_bf16 v[88:91], v[180:183], v[196:199], v[88:91]
	v_mfma_f32_16x16x32_bf16 v[80:83], v[172:175], v[206:209], v[80:83]
	v_mfma_f32_16x16x32_bf16 v[72:75], v[180:183], v[206:209], v[72:75]
	v_mfma_f32_16x16x32_bf16 v[68:71], v[172:175], v[214:217], v[68:71]
	v_mfma_f32_16x16x32_bf16 v[64:67], v[180:183], v[214:217], v[64:67]
	v_mfma_f32_16x16x32_bf16 v[112:115], v[176:179], v[192:195], v[112:115]
	v_mfma_f32_16x16x32_bf16 v[104:107], v[184:187], v[192:195], v[104:107]
	v_mfma_f32_16x16x32_bf16 v[96:99], v[176:179], v[200:203], v[96:99]
	v_mfma_f32_16x16x32_bf16 v[88:91], v[184:187], v[200:203], v[88:91]
	v_mfma_f32_16x16x32_bf16 v[80:83], v[176:179], v[210:213], v[80:83]
	v_mfma_f32_16x16x32_bf16 v[72:75], v[184:187], v[210:213], v[72:75]
	v_mfma_f32_16x16x32_bf16 v[68:71], v[176:179], v[218:221], v[68:71]
	v_mfma_f32_16x16x32_bf16 v[64:67], v[184:187], v[218:221], v[64:67]
	s_barrier
; #define PG8_STAGE(bufoff, gbase, voff) do { _Pragma("unroll") for (int _i = 0; _i < 2; ++_i) \
;         __builtin_amdgcn_global_load_lds((const unsigned*)((const char*)(gbase) + (voff)[_i]), (PG8_LAS unsigned*)(lds + (bufoff) + ldsw + _i * 8192), 16, 0, 0); } while (0)
; #define PG8_LDA(dst, b, h) do { _Pragma("unroll") for (int m = 0; m < 4; ++m) _Pragma("unroll") for (int k = 0; k < 2; ++k) dst[m][k] = *(const PG8_LAS bf16x8*)(lds + PG8_SA(b, h) + aoff + m * 2048 + k * 1024); } while (0)
; #define PG8_MMA(ai, bj, At, Bt) do { __builtin_amdgcn_s_setprio(1); _Pragma("unroll") for (int m = 0; m < 4; ++m) _Pragma("unroll") for (int n = 0; n < 2; ++n) _Pragma("unroll") for (int k = 0; k < 2; ++k) \
;         acc[ai][bj][m][n] = __builtin_amdgcn_mfma_f32_16x16x32_bf16(Bt[n][k], At[m][k], acc[ai][bj][m][n], 0, 0, 0); __builtin_amdgcn_s_setprio(0); } while (0)
; #define PG8_WAIT_V(n) asm volatile("s_waitcnt vmcnt(" #n ")" ::: "memory")
; #define PG8_WAIT_L(n) asm volatile("s_waitcnt lgkmcnt(" #n ")" ::: "memory")
; #define PG8_BAR __builtin_amdgcn_s_barrier()
; #define PG8_SCHED __builtin_amdgcn_sched_barrier(0)
; template <class Epi, class Sched, bool ALIGN_EPI = false, bool SP2 = false>
; __device__ __forceinline__ void gemm_phase(PG8_LAS unsigned char* lds, const Gemm g, const Sched& S, const Epi& E, const int wv0) {
;     ...
;             PG8_LDA(At, 1, 1); PG8_STAGE(PG8_SB(1, 0), b3, voffB); PG8_STAGE(PG8_SB(1, 1), b3 + hstepB, voffB); PG8_STAGE(PG8_SA(1, 0), a3, voffA);
;             PG8_WAIT_V(8); PG8_WAIT_L(0); PG8_BAR; PG8_MMA(1, 0, At, B0); PG8_MMA(1, 1, At, B1); PG8_BAR; PG8_SCHED;
;     ...
;         if constexpr (ALIGN_EPI) { if (wr == 0) PG8_BAR; }
	ds_read_b128 v[188:191], v154 offset:49152
	ds_read_b128 v[192:195], v154 offset:50176
	ds_read_b128 v[196:199], v154 offset:51200
	ds_read_b128 v[200:203], v154 offset:52224
	ds_read_b128 v[206:209], v154 offset:53248
	ds_read_b128 v[210:213], v154 offset:54272
	ds_read_b128 v[214:217], v154 offset:55296
	ds_read_b128 v[218:221], v154 offset:56320
	s_add_i32 s36, s39, s47
	s_mov_b32 m0, s36
	v_lshl_add_u64 v[146:147], v[146:147], 0, s[14:15]
	global_load_lds_dwordx4 v[146:147], off
	s_add_i32 m0, s36, 0x2000
	s_add_u32 s34, s34, 0x80080
	v_lshl_add_u64 v[146:147], v[222:223], 0, s[14:15]
	s_addc_u32 s35, s35, 0
	s_add_i32 s36, s68, s47
	global_load_lds_dwordx4 v[146:147], off
	v_lshl_add_u64 v[146:147], s[34:35], 0, v[132:133]
	s_mov_b32 m0, s36
	s_nop 0
	global_load_lds_dwordx4 v[146:147], off
	v_lshl_add_u64 v[146:147], s[34:35], 0, v[128:129]
	s_add_i32 m0, s36, 0x2000
	s_nop 0
	global_load_lds_dwordx4 v[146:147], off
	v_lshl_add_u64 v[146:147], v[224:225], 0, s[14:15]
	s_mov_b32 m0, s58
	s_nop 0
	global_load_lds_dwordx4 v[146:147], off
	v_lshl_add_u64 v[146:147], v[226:227], 0, s[14:15]
	s_mov_b32 m0, s59
	s_nop 0
	global_load_lds_dwordx4 v[146:147], off
	s_waitcnt vmcnt(8)
	s_waitcnt lgkmcnt(0)
	s_barrier
	v_mfma_f32_16x16x32_bf16 v[60:63], v[156:159], v[188:191], v[60:63]
	v_mfma_f32_16x16x32_bf16 v[56:59], v[164:167], v[188:191], v[56:59]
	v_mfma_f32_16x16x32_bf16 v[52:55], v[156:159], v[196:199], v[52:55]
	v_mfma_f32_16x16x32_bf16 v[44:47], v[164:167], v[196:199], v[44:47]
	v_mfma_f32_16x16x32_bf16 v[36:39], v[156:159], v[206:209], v[36:39]
	v_mfma_f32_16x16x32_bf16 v[28:31], v[164:167], v[206:209], v[28:31]
	v_mfma_f32_16x16x32_bf16 v[20:23], v[156:159], v[214:217], v[20:23]
	v_mfma_f32_16x16x32_bf16 v[12:15], v[164:167], v[214:217], v[12:15]
	v_mfma_f32_16x16x32_bf16 v[60:63], v[160:163], v[192:195], v[60:63]
	v_mfma_f32_16x16x32_bf16 v[56:59], v[168:171], v[192:195], v[56:59]
	v_mfma_f32_16x16x32_bf16 v[52:55], v[160:163], v[200:203], v[52:55]
	v_mfma_f32_16x16x32_bf16 v[44:47], v[168:171], v[200:203], v[44:47]
	v_mfma_f32_16x16x32_bf16 v[36:39], v[160:163], v[210:213], v[36:39]
	v_mfma_f32_16x16x32_bf16 v[28:31], v[168:171], v[210:213], v[28:31]
	v_mfma_f32_16x16x32_bf16 v[20:23], v[160:163], v[218:221], v[20:23]
	v_mfma_f32_16x16x32_bf16 v[12:15], v[168:171], v[218:221], v[12:15]
	v_mfma_f32_16x16x32_bf16 v[48:51], v[172:175], v[188:191], v[48:51]
	v_mfma_f32_16x16x32_bf16 v[40:43], v[180:183], v[188:191], v[40:43]
	v_mfma_f32_16x16x32_bf16 v[32:35], v[172:175], v[196:199], v[32:35]
	v_mfma_f32_16x16x32_bf16 v[24:27], v[180:183], v[196:199], v[24:27]
	v_mfma_f32_16x16x32_bf16 v[16:19], v[172:175], v[206:209], v[16:19]
	v_mfma_f32_16x16x32_bf16 v[8:11], v[180:183], v[206:209], v[8:11]
	v_mfma_f32_16x16x32_bf16 v[4:7], v[172:175], v[214:217], v[4:7]
	v_mfma_f32_16x16x32_bf16 v[0:3], v[180:183], v[214:217], v[0:3]
	v_mfma_f32_16x16x32_bf16 v[48:51], v[176:179], v[192:195], v[48:51]
	v_mfma_f32_16x16x32_bf16 v[40:43], v[184:187], v[192:195], v[40:43]
	v_mfma_f32_16x16x32_bf16 v[32:35], v[176:179], v[200:203], v[32:35]
	v_mfma_f32_16x16x32_bf16 v[24:27], v[184:187], v[200:203], v[24:27]
	v_mfma_f32_16x16x32_bf16 v[16:19], v[176:179], v[210:213], v[16:19]
	v_mfma_f32_16x16x32_bf16 v[8:11], v[184:187], v[210:213], v[8:11]
	v_mfma_f32_16x16x32_bf16 v[4:7], v[176:179], v[218:221], v[4:7]
	v_mfma_f32_16x16x32_bf16 v[0:3], v[184:187], v[218:221], v[0:3]
	s_barrier
	s_add_i32 s38, s38, 2
	s_add_u32 s21, s21, 0x100
	s_addc_u32 s23, s23, 0
	s_add_u32 s30, s30, 0x100
	s_addc_u32 s31, s31, 0
	s_cmp_gt_u32 s38, 29
	s_cbranch_scc0 .LBB0_82
	s_and_b64 vcc, exec, s[18:19]
	s_cbranch_vccz .LBB0_85
	s_barrier

; #define PG8_STAGE(bufoff, gbase, voff) do { _Pragma("unroll") for (int _i = 0; _i < 2; ++_i) \
;         __builtin_amdgcn_global_load_lds((const unsigned*)((const char*)(gbase) + (voff)[_i]), (PG8_LAS unsigned*)(lds + (bufoff) + ldsw + _i * 8192), 16, 0, 0); } while (0)
; #define PG8_LDA(dst, b, h) do { _Pragma("unroll") for (int m = 0; m < 4; ++m) _Pragma("unroll") for (int k = 0; k < 2; ++k) dst[m][k] = *(const PG8_LAS bf16x8*)(lds + PG8_SA(b, h) + aoff + m * 2048 + k * 1024); } while (0)
; #define PG8_LDB(dst, b, h) do { _Pragma("unroll") for (int n = 0; n < 2; ++n) _Pragma("unroll") for (int k = 0; k < 2; ++k) dst[n][k] = *(const PG8_LAS bf16x8*)(lds + PG8_SB(b, h) + boff + n * 2048 + k * 1024); } while (0)
; #define PG8_MMA(ai, bj, At, Bt) do { __builtin_amdgcn_s_setprio(1); _Pragma("unroll") for (int m = 0; m < 4; ++m) _Pragma("unroll") for (int n = 0; n < 2; ++n) _Pragma("unroll") for (int k = 0; k < 2; ++k) \
;         acc[ai][bj][m][n] = __builtin_amdgcn_mfma_f32_16x16x32_bf16(Bt[n][k], At[m][k], acc[ai][bj][m][n], 0, 0, 0); __builtin_amdgcn_s_setprio(0); } while (0)
; #define PG8_WAIT_V(n) asm volatile("s_waitcnt vmcnt(" #n ")" ::: "memory")
; #define PG8_WAIT_L(n) asm volatile("s_waitcnt lgkmcnt(" #n ")" ::: "memory")
; #define PG8_BAR __builtin_amdgcn_s_barrier()
; template <class Epi, class Sched, bool ALIGN_EPI = false, bool SP2 = false>
; __device__ __forceinline__ void gemm_phase(PG8_LAS unsigned char* lds, const Gemm g, const Sched& S, const Epi& E, const int wv0) {
;     ...
;             const bool last = (t == nt - 2);
;             const char* a1 = cA + (size_t)(t + 1) * kstep;
;             const char* a2 = last ? nA : cA + (size_t)(t + 2) * kstep; const char* b2 = last ? nB : cB + (size_t)(t + 2) * kstep;
;             const char* a3 = a2 + kstep; const char* b3 = b2 + kstep;
;             if constexpr (SP2) {
;             PG8_LDB(B0, 0, 0); PG8_LDB(B1, 0, 1); PG8_SCHED; PG8_LDA(At, 0, 0); PG8_STAGE(PG8_SA(1, 1), a1 + hstepA, voffA);
;             PG8_WAIT_V(8); PG8_WAIT_L(0); PG8_BAR; PG8_MMA(0, 0, At, B0); PG8_MMA(0, 1, At, B1); PG8_BAR; PG8_SCHED;
;             PG8_LDA(At, 0, 1); PG8_STAGE(PG8_SB(0, 0), b2, voffB); PG8_STAGE(PG8_SB(0, 1), b2 + hstepB, voffB); PG8_STAGE(PG8_SA(0, 0), a2, voffA);
;             PG8_WAIT_V(8); PG8_WAIT_L(0); PG8_BAR; PG8_MMA(1, 0, At, B0); PG8_MMA(1, 1, At, B1); PG8_BAR; PG8_SCHED;
.LBB0_667:
	ds_read_b128 v[144:147], v153
	ds_read_b128 v[156:159], v153 offset:1024
	ds_read_b128 v[160:163], v153 offset:2048
	ds_read_b128 v[164:167], v153 offset:3072
	ds_read_b128 v[168:171], v154
	ds_read_b128 v[172:175], v154 offset:1024
	ds_read_b128 v[176:179], v154 offset:2048
	ds_read_b128 v[180:183], v154 offset:3072
	ds_read_b128 v[184:187], v155
	ds_read_b128 v[188:191], v155 offset:1024
	ds_read_b128 v[192:195], v155 offset:2048
	ds_read_b128 v[196:199], v155 offset:3072
	ds_read_b128 v[200:203], v155 offset:4096
	ds_read_b128 v[206:209], v155 offset:5120
	ds_read_b128 v[210:213], v155 offset:6144
	ds_read_b128 v[214:217], v155 offset:7168
	s_add_u32 s24, s22, 0xfff80080
	s_addc_u32 s25, s23, -1
	s_cmp_eq_u32 s50, 28
	s_cselect_b32 s27, s17, s25
	s_cselect_b32 s26, s16, s24
	s_cselect_b32 s25, s19, s15
	s_cselect_b32 s24, s18, s13
	s_add_i32 m0, s21, 0xc000
	v_lshl_add_u64 v[148:149], s[22:23], 0, v[138:139]
	global_load_lds_dwordx4 v[148:149], off
	v_lshl_add_u64 v[148:149], s[22:23], 0, v[136:137]
	s_add_i32 m0, s21, 0xe000
	s_nop 0
	global_load_lds_dwordx4 v[148:149], off
	s_waitcnt vmcnt(8)
	s_waitcnt lgkmcnt(0)
	s_barrier
	v_mfma_f32_16x16x32_bf16 v[124:127], v[144:147], v[184:187], v[124:127]
	v_mfma_f32_16x16x32_bf16 v[120:123], v[160:163], v[184:187], v[120:123]
	v_mfma_f32_16x16x32_bf16 v[116:119], v[144:147], v[192:195], v[116:119]
	v_mfma_f32_16x16x32_bf16 v[112:115], v[160:163], v[192:195], v[112:115]
	v_mfma_f32_16x16x32_bf16 v[92:95], v[144:147], v[200:203], v[92:95]
	v_mfma_f32_16x16x32_bf16 v[88:91], v[160:163], v[200:203], v[88:91]
	v_mfma_f32_16x16x32_bf16 v[84:87], v[144:147], v[210:213], v[84:87]
	v_mfma_f32_16x16x32_bf16 v[80:83], v[160:163], v[210:213], v[80:83]
	v_mfma_f32_16x16x32_bf16 v[124:127], v[156:159], v[188:191], v[124:127]
	v_mfma_f32_16x16x32_bf16 v[120:123], v[164:167], v[188:191], v[120:123]
	v_mfma_f32_16x16x32_bf16 v[116:119], v[156:159], v[196:199], v[116:119]
	v_mfma_f32_16x16x32_bf16 v[112:115], v[164:167], v[196:199], v[112:115]
	v_mfma_f32_16x16x32_bf16 v[92:95], v[156:159], v[206:209], v[92:95]
	v_mfma_f32_16x16x32_bf16 v[88:91], v[164:167], v[206:209], v[88:91]
	v_mfma_f32_16x16x32_bf16 v[84:87], v[156:159], v[214:217], v[84:87]
	v_mfma_f32_16x16x32_bf16 v[80:83], v[164:167], v[214:217], v[80:83]
	v_mfma_f32_16x16x32_bf16 v[108:111], v[168:171], v[184:187], v[108:111]
	v_mfma_f32_16x16x32_bf16 v[104:107], v[176:179], v[184:187], v[104:107]
	v_mfma_f32_16x16x32_bf16 v[100:103], v[168:171], v[192:195], v[100:103]
	v_mfma_f32_16x16x32_bf16 v[96:99], v[176:179], v[192:195], v[96:99]
	v_mfma_f32_16x16x32_bf16 v[76:79], v[168:171], v[200:203], v[76:79]
	v_mfma_f32_16x16x32_bf16 v[72:75], v[176:179], v[200:203], v[72:75]
	v_mfma_f32_16x16x32_bf16 v[68:71], v[168:171], v[210:213], v[68:71]
	v_mfma_f32_16x16x32_bf16 v[64:67], v[176:179], v[210:213], v[64:67]
	v_mfma_f32_16x16x32_bf16 v[108:111], v[172:175], v[188:191], v[108:111]
	v_mfma_f32_16x16x32_bf16 v[104:107], v[180:183], v[188:191], v[104:107]
	v_mfma_f32_16x16x32_bf16 v[100:103], v[172:175], v[196:199], v[100:103]
	v_mfma_f32_16x16x32_bf16 v[96:99], v[180:183], v[196:199], v[96:99]
	v_mfma_f32_16x16x32_bf16 v[76:79], v[172:175], v[206:209], v[76:79]
	v_mfma_f32_16x16x32_bf16 v[72:75], v[180:183], v[206:209], v[72:75]
	v_mfma_f32_16x16x32_bf16 v[68:71], v[172:175], v[214:217], v[68:71]
	v_mfma_f32_16x16x32_bf16 v[64:67], v[180:183], v[214:217], v[64:67]
	s_barrier
	ds_read_b128 v[184:187], v155 offset:16384
	ds_read_b128 v[188:191], v155 offset:17408
	ds_read_b128 v[192:195], v155 offset:18432
	ds_read_b128 v[196:199], v155 offset:19456
	ds_read_b128 v[200:203], v155 offset:20480
	ds_read_b128 v[206:209], v155 offset:21504
	ds_read_b128 v[210:213], v155 offset:22528
	ds_read_b128 v[214:217], v155 offset:23552
	s_add_i32 s51, s47, s37
	s_mov_b32 m0, s51
	v_lshl_add_u64 v[148:149], s[24:25], 0, v[130:131]
	global_load_lds_dwordx4 v[148:149], off
	s_add_i32 m0, s51, 0x2000
	s_add_u32 s52, s24, 0x80000
	v_lshl_add_u64 v[218:219], s[24:25], 0, v[134:135]
	s_addc_u32 s53, s25, 0
	s_add_i32 s51, s48, s37
	global_load_lds_dwordx4 v[218:219], off
	v_lshl_add_u64 v[220:221], s[52:53], 0, v[130:131]
	s_mov_b32 m0, s51
	v_lshl_add_u64 v[222:223], s[26:27], 0, v[132:133]
	global_load_lds_dwordx4 v[220:221], off
	v_lshl_add_u64 v[220:221], s[52:53], 0, v[134:135]
	s_add_i32 m0, s51, 0x2000
	s_nop 0
	global_load_lds_dwordx4 v[220:221], off
	v_lshl_add_u64 v[220:221], s[26:27], 0, v[128:129]
	s_mov_b32 m0, s21
	s_nop 0
	global_load_lds_dwordx4 v[220:221], off
	s_mov_b32 m0, s38
	s_nop 0
	global_load_lds_dwordx4 v[222:223], off
	s_waitcnt vmcnt(8)
	s_waitcnt lgkmcnt(0)
	s_barrier
; #define PG8_STAGE(bufoff, gbase, voff) do { _Pragma("unroll") for (int _i = 0; _i < 2; ++_i) \
;         __builtin_amdgcn_global_load_lds((const unsigned*)((const char*)(gbase) + (voff)[_i]), (PG8_LAS unsigned*)(lds + (bufoff) + ldsw + _i * 8192), 16, 0, 0); } while (0)
; #define PG8_LDA(dst, b, h) do { _Pragma("unroll") for (int m = 0; m < 4; ++m) _Pragma("unroll") for (int k = 0; k < 2; ++k) dst[m][k] = *(const PG8_LAS bf16x8*)(lds + PG8_SA(b, h) + aoff + m * 2048 + k * 1024); } while (0)
; #define PG8_LDB(dst, b, h) do { _Pragma("unroll") for (int n = 0; n < 2; ++n) _Pragma("unroll") for (int k = 0; k < 2; ++k) dst[n][k] = *(const PG8_LAS bf16x8*)(lds + PG8_SB(b, h) + boff + n * 2048 + k * 1024); } while (0)
; #define PG8_MMA(ai, bj, At, Bt) do { __builtin_amdgcn_s_setprio(1); _Pragma("unroll") for (int m = 0; m < 4; ++m) _Pragma("unroll") for (int n = 0; n < 2; ++n) _Pragma("unroll") for (int k = 0; k < 2; ++k) \
;         acc[ai][bj][m][n] = __builtin_amdgcn_mfma_f32_16x16x32_bf16(Bt[n][k], At[m][k], acc[ai][bj][m][n], 0, 0, 0); __builtin_amdgcn_s_setprio(0); } while (0)
; #define PG8_WAIT_V(n) asm volatile("s_waitcnt vmcnt(" #n ")" ::: "memory")
; #define PG8_WAIT_L(n) asm volatile("s_waitcnt lgkmcnt(" #n ")" ::: "memory")
; #define PG8_BAR __builtin_amdgcn_s_barrier()
; #define PG8_SCHED __builtin_amdgcn_sched_barrier(0)
; template <class Epi, class Sched, bool ALIGN_EPI = false, bool SP2 = false>
; __device__ __forceinline__ void gemm_phase(PG8_LAS unsigned char* lds, const Gemm g, const Sched& S, const Epi& E, const int wv0) {
;     ...
;             PG8_WAIT_V(8); PG8_WAIT_L(0); PG8_BAR; PG8_MMA(1, 0, At, B0); PG8_MMA(1, 1, At, B1); PG8_BAR; PG8_SCHED;
;             PG8_LDB(B0, 1, 0); PG8_LDB(B1, 1, 1); PG8_SCHED; PG8_LDA(At, 1, 0); PG8_STAGE(PG8_SA(0, 1), a2 + hstepA, voffA);
;             PG8_WAIT_V(8); PG8_WAIT_L(0); PG8_BAR; PG8_MMA(0, 0, At, B0); PG8_MMA(0, 1, At, B1); PG8_BAR; PG8_SCHED;
	v_mfma_f32_16x16x32_bf16 v[60:63], v[144:147], v[184:187], v[60:63]
	v_mfma_f32_16x16x32_bf16 v[56:59], v[160:163], v[184:187], v[56:59]
	v_mfma_f32_16x16x32_bf16 v[52:55], v[144:147], v[192:195], v[52:55]
	v_mfma_f32_16x16x32_bf16 v[48:51], v[160:163], v[192:195], v[48:51]
	v_mfma_f32_16x16x32_bf16 v[28:31], v[144:147], v[200:203], v[28:31]
	v_mfma_f32_16x16x32_bf16 v[24:27], v[160:163], v[200:203], v[24:27]
	v_mfma_f32_16x16x32_bf16 v[20:23], v[144:147], v[210:213], v[20:23]
	v_mfma_f32_16x16x32_bf16 v[16:19], v[160:163], v[210:213], v[16:19]
	v_mfma_f32_16x16x32_bf16 v[60:63], v[156:159], v[188:191], v[60:63]
	v_mfma_f32_16x16x32_bf16 v[56:59], v[164:167], v[188:191], v[56:59]
	v_mfma_f32_16x16x32_bf16 v[52:55], v[156:159], v[196:199], v[52:55]
	v_mfma_f32_16x16x32_bf16 v[48:51], v[164:167], v[196:199], v[48:51]
	v_mfma_f32_16x16x32_bf16 v[28:31], v[156:159], v[206:209], v[28:31]
	v_mfma_f32_16x16x32_bf16 v[24:27], v[164:167], v[206:209], v[24:27]
	v_mfma_f32_16x16x32_bf16 v[20:23], v[156:159], v[214:217], v[20:23]
	v_mfma_f32_16x16x32_bf16 v[16:19], v[164:167], v[214:217], v[16:19]
	v_mfma_f32_16x16x32_bf16 v[44:47], v[168:171], v[184:187], v[44:47]
	v_mfma_f32_16x16x32_bf16 v[40:43], v[176:179], v[184:187], v[40:43]
	v_mfma_f32_16x16x32_bf16 v[36:39], v[168:171], v[192:195], v[36:39]
	v_mfma_f32_16x16x32_bf16 v[32:35], v[176:179], v[192:195], v[32:35]
	v_mfma_f32_16x16x32_bf16 v[12:15], v[168:171], v[200:203], v[12:15]
	v_mfma_f32_16x16x32_bf16 v[8:11], v[176:179], v[200:203], v[8:11]
	v_mfma_f32_16x16x32_bf16 v[4:7], v[168:171], v[210:213], v[4:7]
	v_mfma_f32_16x16x32_bf16 v[0:3], v[176:179], v[210:213], v[0:3]
	v_mfma_f32_16x16x32_bf16 v[44:47], v[172:175], v[188:191], v[44:47]
	v_mfma_f32_16x16x32_bf16 v[40:43], v[180:183], v[188:191], v[40:43]
	v_mfma_f32_16x16x32_bf16 v[36:39], v[172:175], v[196:199], v[36:39]
	v_mfma_f32_16x16x32_bf16 v[32:35], v[180:183], v[196:199], v[32:35]
	v_mfma_f32_16x16x32_bf16 v[12:15], v[172:175], v[206:209], v[12:15]
	v_mfma_f32_16x16x32_bf16 v[8:11], v[180:183], v[206:209], v[8:11]
	v_mfma_f32_16x16x32_bf16 v[4:7], v[172:175], v[214:217], v[4:7]
	v_mfma_f32_16x16x32_bf16 v[0:3], v[180:183], v[214:217], v[0:3]
	s_barrier
	s_add_i32 s51, 0, 0x18000
	s_add_i32 s52, 0, 0x1c000
	v_add_u32_e32 v164, s51, v151
	v_add_u32_e32 v180, s52, v151
	ds_read_b128 v[144:147], v164
	ds_read_b128 v[156:159], v164 offset:1024
	ds_read_b128 v[160:163], v164 offset:2048
	ds_read_b128 v[164:167], v164 offset:3072
	ds_read_b128 v[168:171], v180
	ds_read_b128 v[172:175], v180 offset:1024
	ds_read_b128 v[176:179], v180 offset:2048
	ds_read_b128 v[180:183], v180 offset:3072
	s_add_u32 s26, s26, 0x80000
	s_addc_u32 s27, s27, 0
	s_mov_b32 m0, s39
	v_lshl_add_u64 v[224:225], s[26:27], 0, v[128:129]
	ds_read_b128 v[184:187], v155 offset:32768
	ds_read_b128 v[188:191], v155 offset:33792
	ds_read_b128 v[192:195], v155 offset:34816
	ds_read_b128 v[196:199], v155 offset:35840
	ds_read_b128 v[200:203], v155 offset:36864
	ds_read_b128 v[206:209], v155 offset:37888
	ds_read_b128 v[210:213], v155 offset:38912
	ds_read_b128 v[214:217], v155 offset:39936
	global_load_lds_dwordx4 v[224:225], off
	v_lshl_add_u64 v[224:225], s[26:27], 0, v[132:133]
	s_mov_b32 m0, s40
	s_nop 0
	global_load_lds_dwordx4 v[224:225], off
	s_waitcnt vmcnt(8)
	s_waitcnt lgkmcnt(0)
	s_barrier
	v_mfma_f32_16x16x32_bf16 v[124:127], v[144:147], v[184:187], v[124:127]
	v_mfma_f32_16x16x32_bf16 v[120:123], v[160:163], v[184:187], v[120:123]
	v_mfma_f32_16x16x32_bf16 v[116:119], v[144:147], v[192:195], v[116:119]
	v_mfma_f32_16x16x32_bf16 v[112:115], v[160:163], v[192:195], v[112:115]
	v_mfma_f32_16x16x32_bf16 v[92:95], v[144:147], v[200:203], v[92:95]
	v_mfma_f32_16x16x32_bf16 v[88:91], v[160:163], v[200:203], v[88:91]
	v_mfma_f32_16x16x32_bf16 v[84:87], v[144:147], v[210:213], v[84:87]
	v_mfma_f32_16x16x32_bf16 v[80:83], v[160:163], v[210:213], v[80:83]
	v_mfma_f32_16x16x32_bf16 v[124:127], v[156:159], v[188:191], v[124:127]
	v_mfma_f32_16x16x32_bf16 v[120:123], v[164:167], v[188:191], v[120:123]
	v_mfma_f32_16x16x32_bf16 v[116:119], v[156:159], v[196:199], v[116:119]
	v_mfma_f32_16x16x32_bf16 v[112:115], v[164:167], v[196:199], v[112:115]
	v_mfma_f32_16x16x32_bf16 v[92:95], v[156:159], v[206:209], v[92:95]
	v_mfma_f32_16x16x32_bf16 v[88:91], v[164:167], v[206:209], v[88:91]
	v_mfma_f32_16x16x32_bf16 v[84:87], v[156:159], v[214:217], v[84:87]
	v_mfma_f32_16x16x32_bf16 v[80:83], v[164:167], v[214:217], v[80:83]
	v_mfma_f32_16x16x32_bf16 v[108:111], v[168:171], v[184:187], v[108:111]
	v_mfma_f32_16x16x32_bf16 v[104:107], v[176:179], v[184:187], v[104:107]
	v_mfma_f32_16x16x32_bf16 v[100:103], v[168:171], v[192:195], v[100:103]
	v_mfma_f32_16x16x32_bf16 v[96:99], v[176:179], v[192:195], v[96:99]
	v_mfma_f32_16x16x32_bf16 v[76:79], v[168:171], v[200:203], v[76:79]
	v_mfma_f32_16x16x32_bf16 v[72:75], v[176:179], v[200:203], v[72:75]
	v_mfma_f32_16x16x32_bf16 v[68:71], v[168:171], v[210:213], v[68:71]
	v_mfma_f32_16x16x32_bf16 v[64:67], v[176:179], v[210:213], v[64:67]
	v_mfma_f32_16x16x32_bf16 v[108:111], v[172:175], v[188:191], v[108:111]
	v_mfma_f32_16x16x32_bf16 v[104:107], v[180:183], v[188:191], v[104:107]
	v_mfma_f32_16x16x32_bf16 v[100:103], v[172:175], v[196:199], v[100:103]
	v_mfma_f32_16x16x32_bf16 v[96:99], v[180:183], v[196:199], v[96:99]
	v_mfma_f32_16x16x32_bf16 v[76:79], v[172:175], v[206:209], v[76:79]
	v_mfma_f32_16x16x32_bf16 v[72:75], v[180:183], v[206:209], v[72:75]
	v_mfma_f32_16x16x32_bf16 v[68:71], v[172:175], v[214:217], v[68:71]
	v_mfma_f32_16x16x32_bf16 v[64:67], v[180:183], v[214:217], v[64:67]
	s_barrier
; #define PG8_STAGE(bufoff, gbase, voff) do { _Pragma("unroll") for (int _i = 0; _i < 2; ++_i) \
;         __builtin_amdgcn_global_load_lds((const unsigned*)((const char*)(gbase) + (voff)[_i]), (PG8_LAS unsigned*)(lds + (bufoff) + ldsw + _i * 8192), 16, 0, 0); } while (0)
; #define PG8_LDA(dst, b, h) do { _Pragma("unroll") for (int m = 0; m < 4; ++m) _Pragma("unroll") for (int k = 0; k < 2; ++k) dst[m][k] = *(const PG8_LAS bf16x8*)(lds + PG8_SA(b, h) + aoff + m * 2048 + k * 1024); } while (0)
; #define PG8_MMA(ai, bj, At, Bt) do { __builtin_amdgcn_s_setprio(1); _Pragma("unroll") for (int m = 0; m < 4; ++m) _Pragma("unroll") for (int n = 0; n < 2; ++n) _Pragma("unroll") for (int k = 0; k < 2; ++k) \
;         acc[ai][bj][m][n] = __builtin_amdgcn_mfma_f32_16x16x32_bf16(Bt[n][k], At[m][k], acc[ai][bj][m][n], 0, 0, 0); __builtin_amdgcn_s_setprio(0); } while (0)
; #define PG8_WAIT_V(n) asm volatile("s_waitcnt vmcnt(" #n ")" ::: "memory")
; #define PG8_WAIT_L(n) asm volatile("s_waitcnt lgkmcnt(" #n ")" ::: "memory")
; #define PG8_BAR __builtin_amdgcn_s_barrier()
; #define PG8_SCHED __builtin_amdgcn_sched_barrier(0)
; template <class Epi, class Sched, bool ALIGN_EPI = false, bool SP2 = false>
; __device__ __forceinline__ void gemm_phase(PG8_LAS unsigned char* lds, const Gemm g, const Sched& S, const Epi& E, const int wv0) {
;     ...
;             PG8_LDA(At, 1, 1); PG8_STAGE(PG8_SB(1, 0), b3, voffB); PG8_STAGE(PG8_SB(1, 1), b3 + hstepB, voffB); PG8_STAGE(PG8_SA(1, 0), a3, voffA);
;             PG8_WAIT_V(8); PG8_WAIT_L(0); PG8_BAR; PG8_MMA(1, 0, At, B0); PG8_MMA(1, 1, At, B1); PG8_BAR; PG8_SCHED;
;     ...
;         if constexpr (ALIGN_EPI) { if (wr == 0) PG8_BAR; }
	ds_read_b128 v[184:187], v155 offset:49152
	ds_read_b128 v[188:191], v155 offset:50176
	ds_read_b128 v[192:195], v155 offset:51200
	ds_read_b128 v[196:199], v155 offset:52224
	ds_read_b128 v[200:203], v155 offset:53248
	ds_read_b128 v[206:209], v155 offset:54272
	ds_read_b128 v[210:213], v155 offset:55296
	ds_read_b128 v[214:217], v155 offset:56320
	s_add_i32 s26, s51, s37
	s_mov_b32 m0, s26
	v_lshl_add_u64 v[148:149], v[148:149], 0, s[8:9]
	global_load_lds_dwordx4 v[148:149], off
	s_add_i32 m0, s26, 0x2000
	s_add_u32 s24, s24, 0x80080
	v_lshl_add_u64 v[148:149], v[218:219], 0, s[8:9]
	s_addc_u32 s25, s25, 0
	s_add_i32 s26, s52, s37
	global_load_lds_dwordx4 v[148:149], off
	v_lshl_add_u64 v[148:149], s[24:25], 0, v[130:131]
	s_mov_b32 m0, s26
	s_nop 0
	global_load_lds_dwordx4 v[148:149], off
	v_lshl_add_u64 v[148:149], s[24:25], 0, v[134:135]
	s_add_i32 m0, s26, 0x2000
	s_nop 0
	global_load_lds_dwordx4 v[148:149], off
	v_lshl_add_u64 v[148:149], v[220:221], 0, s[8:9]
	s_mov_b32 m0, s44
	s_nop 0
	global_load_lds_dwordx4 v[148:149], off
	v_lshl_add_u64 v[148:149], v[222:223], 0, s[8:9]
	s_mov_b32 m0, s45
	s_nop 0
	global_load_lds_dwordx4 v[148:149], off
	s_waitcnt vmcnt(8)
	s_waitcnt lgkmcnt(0)
	s_barrier
	v_mfma_f32_16x16x32_bf16 v[60:63], v[144:147], v[184:187], v[60:63]
	v_mfma_f32_16x16x32_bf16 v[56:59], v[160:163], v[184:187], v[56:59]
	v_mfma_f32_16x16x32_bf16 v[52:55], v[144:147], v[192:195], v[52:55]
	v_mfma_f32_16x16x32_bf16 v[48:51], v[160:163], v[192:195], v[48:51]
	v_mfma_f32_16x16x32_bf16 v[28:31], v[144:147], v[200:203], v[28:31]
	v_mfma_f32_16x16x32_bf16 v[24:27], v[160:163], v[200:203], v[24:27]
	v_mfma_f32_16x16x32_bf16 v[20:23], v[144:147], v[210:213], v[20:23]
	v_mfma_f32_16x16x32_bf16 v[16:19], v[160:163], v[210:213], v[16:19]
	v_mfma_f32_16x16x32_bf16 v[60:63], v[156:159], v[188:191], v[60:63]
	v_mfma_f32_16x16x32_bf16 v[56:59], v[164:167], v[188:191], v[56:59]
	v_mfma_f32_16x16x32_bf16 v[52:55], v[156:159], v[196:199], v[52:55]
	v_mfma_f32_16x16x32_bf16 v[48:51], v[164:167], v[196:199], v[48:51]
	v_mfma_f32_16x16x32_bf16 v[28:31], v[156:159], v[206:209], v[28:31]
	v_mfma_f32_16x16x32_bf16 v[24:27], v[164:167], v[206:209], v[24:27]
	v_mfma_f32_16x16x32_bf16 v[20:23], v[156:159], v[214:217], v[20:23]
	v_mfma_f32_16x16x32_bf16 v[16:19], v[164:167], v[214:217], v[16:19]
	v_mfma_f32_16x16x32_bf16 v[44:47], v[168:171], v[184:187], v[44:47]
	v_mfma_f32_16x16x32_bf16 v[40:43], v[176:179], v[184:187], v[40:43]
	v_mfma_f32_16x16x32_bf16 v[36:39], v[168:171], v[192:195], v[36:39]
	v_mfma_f32_16x16x32_bf16 v[32:35], v[176:179], v[192:195], v[32:35]
	v_mfma_f32_16x16x32_bf16 v[12:15], v[168:171], v[200:203], v[12:15]
	v_mfma_f32_16x16x32_bf16 v[8:11], v[176:179], v[200:203], v[8:11]
	v_mfma_f32_16x16x32_bf16 v[4:7], v[168:171], v[210:213], v[4:7]
	v_mfma_f32_16x16x32_bf16 v[0:3], v[176:179], v[210:213], v[0:3]
	v_mfma_f32_16x16x32_bf16 v[44:47], v[172:175], v[188:191], v[44:47]
	v_mfma_f32_16x16x32_bf16 v[40:43], v[180:183], v[188:191], v[40:43]
	v_mfma_f32_16x16x32_bf16 v[36:39], v[172:175], v[196:199], v[36:39]
	v_mfma_f32_16x16x32_bf16 v[32:35], v[180:183], v[196:199], v[32:35]
	v_mfma_f32_16x16x32_bf16 v[12:15], v[172:175], v[206:209], v[12:15]
	v_mfma_f32_16x16x32_bf16 v[8:11], v[180:183], v[206:209], v[8:11]
	v_mfma_f32_16x16x32_bf16 v[4:7], v[172:175], v[214:217], v[4:7]
	v_mfma_f32_16x16x32_bf16 v[0:3], v[180:183], v[214:217], v[0:3]
	s_barrier
	s_add_i32 s50, s50, 2
	s_add_u32 s13, s13, 0x100
	s_addc_u32 s15, s15, 0
	s_add_u32 s22, s22, 0x100
	s_addc_u32 s23, s23, 0
	s_cmp_gt_u32 s50, 29
	s_cbranch_scc0 .LBB0_667
	s_and_b64 vcc, exec, s[10:11]
	s_cbranch_vccz .LBB0_670
	s_barrier

; #define PG8_STAGE(bufoff, gbase, voff) do { _Pragma("unroll") for (int _i = 0; _i < 2; ++_i) \
;         __builtin_amdgcn_global_load_lds((const unsigned*)((const char*)(gbase) + (voff)[_i]), (PG8_LAS unsigned*)(lds + (bufoff) + ldsw + _i * 8192), 16, 0, 0); } while (0)
; #define PG8_LDA(dst, b, h) do { _Pragma("unroll") for (int m = 0; m < 4; ++m) _Pragma("unroll") for (int k = 0; k < 2; ++k) dst[m][k] = *(const PG8_LAS bf16x8*)(lds + PG8_SA(b, h) + aoff + m * 2048 + k * 1024); } while (0)
; #define PG8_LDB(dst, b, h) do { _Pragma("unroll") for (int n = 0; n < 2; ++n) _Pragma("unroll") for (int k = 0; k < 2; ++k) dst[n][k] = *(const PG8_LAS bf16x8*)(lds + PG8_SB(b, h) + boff + n * 2048 + k * 1024); } while (0)
; #define PG8_MMA(ai, bj, At, Bt) do { __builtin_amdgcn_s_setprio(1); _Pragma("unroll") for (int m = 0; m < 4; ++m) _Pragma("unroll") for (int n = 0; n < 2; ++n) _Pragma("unroll") for (int k = 0; k < 2; ++k) \
;         acc[ai][bj][m][n] = __builtin_amdgcn_mfma_f32_16x16x32_bf16(Bt[n][k], At[m][k], acc[ai][bj][m][n], 0, 0, 0); __builtin_amdgcn_s_setprio(0); } while (0)
; #define PG8_WAIT_V(n) asm volatile("s_waitcnt vmcnt(" #n ")" ::: "memory")
; #define PG8_WAIT_L(n) asm volatile("s_waitcnt lgkmcnt(" #n ")" ::: "memory")
; #define PG8_BAR __builtin_amdgcn_s_barrier()
; template <class Epi, class Sched, bool ALIGN_EPI = false, bool SP2 = false>
; __device__ __forceinline__ void gemm_phase(PG8_LAS unsigned char* lds, const Gemm g, const Sched& S, const Epi& E, const int wv0) {
;     ...
;             const bool last = (t == nt - 2);
;             const char* a1 = cA + (size_t)(t + 1) * kstep;
;             const char* a2 = last ? nA : cA + (size_t)(t + 2) * kstep; const char* b2 = last ? nB : cB + (size_t)(t + 2) * kstep;
;             const char* a3 = a2 + kstep; const char* b3 = b2 + kstep;
;             if constexpr (SP2) {
;             PG8_LDB(B0, 0, 0); PG8_LDB(B1, 0, 1); PG8_SCHED; PG8_LDA(At, 0, 0); PG8_STAGE(PG8_SA(1, 1), a1 + hstepA, voffA);
;             PG8_WAIT_V(8); PG8_WAIT_L(0); PG8_BAR; PG8_MMA(0, 0, At, B0); PG8_MMA(0, 1, At, B1); PG8_BAR; PG8_SCHED;
;             PG8_LDA(At, 0, 1); PG8_STAGE(PG8_SB(0, 0), b2, voffB); PG8_STAGE(PG8_SB(0, 1), b2 + hstepB, voffB); PG8_STAGE(PG8_SA(0, 0), a2, voffA);
;             PG8_WAIT_V(8); PG8_WAIT_L(0); PG8_BAR; PG8_MMA(1, 0, At, B0); PG8_MMA(1, 1, At, B1); PG8_BAR; PG8_SCHED;
.LBB0_790:
	ds_read_b128 v[152:155], v149
	ds_read_b128 v[156:159], v149 offset:1024
	ds_read_b128 v[160:163], v149 offset:2048
	ds_read_b128 v[164:167], v149 offset:3072
	ds_read_b128 v[168:171], v150
	ds_read_b128 v[172:175], v150 offset:1024
	ds_read_b128 v[176:179], v150 offset:2048
	ds_read_b128 v[180:183], v150 offset:3072
	ds_read_b128 v[184:187], v151
	ds_read_b128 v[188:191], v151 offset:1024
	ds_read_b128 v[192:195], v151 offset:2048
	ds_read_b128 v[196:199], v151 offset:3072
	ds_read_b128 v[200:203], v151 offset:4096
	ds_read_b128 v[206:209], v151 offset:5120
	ds_read_b128 v[210:213], v151 offset:6144
	ds_read_b128 v[214:217], v151 offset:7168
	s_add_u32 s22, s20, 0xfff80080
	s_addc_u32 s23, s21, -1
	s_cmp_eq_u32 s50, 28
	s_cselect_b32 s25, s15, s23
	s_cselect_b32 s24, s14, s22
	s_cselect_b32 s23, s17, s13
	s_cselect_b32 s22, s16, s11
	s_add_i32 m0, s19, 0xc000
	v_lshl_add_u64 v[144:145], s[20:21], 0, v[138:139]
	global_load_lds_dwordx4 v[144:145], off
	v_lshl_add_u64 v[144:145], s[20:21], 0, v[136:137]
	s_add_i32 m0, s19, 0xe000
	s_nop 0
	global_load_lds_dwordx4 v[144:145], off
	s_waitcnt vmcnt(8)
	s_waitcnt lgkmcnt(0)
	s_barrier
	v_mfma_f32_16x16x32_bf16 v[124:127], v[152:155], v[184:187], v[124:127]
	v_mfma_f32_16x16x32_bf16 v[120:123], v[160:163], v[184:187], v[120:123]
	v_mfma_f32_16x16x32_bf16 v[108:111], v[152:155], v[192:195], v[108:111]
	v_mfma_f32_16x16x32_bf16 v[104:107], v[160:163], v[192:195], v[104:107]
	v_mfma_f32_16x16x32_bf16 v[92:95], v[152:155], v[200:203], v[92:95]
	v_mfma_f32_16x16x32_bf16 v[88:91], v[160:163], v[200:203], v[88:91]
	v_mfma_f32_16x16x32_bf16 v[76:79], v[152:155], v[210:213], v[76:79]
	v_mfma_f32_16x16x32_bf16 v[72:75], v[160:163], v[210:213], v[72:75]
	v_mfma_f32_16x16x32_bf16 v[124:127], v[156:159], v[188:191], v[124:127]
	v_mfma_f32_16x16x32_bf16 v[120:123], v[164:167], v[188:191], v[120:123]
	v_mfma_f32_16x16x32_bf16 v[108:111], v[156:159], v[196:199], v[108:111]
	v_mfma_f32_16x16x32_bf16 v[104:107], v[164:167], v[196:199], v[104:107]
	v_mfma_f32_16x16x32_bf16 v[92:95], v[156:159], v[206:209], v[92:95]
	v_mfma_f32_16x16x32_bf16 v[88:91], v[164:167], v[206:209], v[88:91]
	v_mfma_f32_16x16x32_bf16 v[76:79], v[156:159], v[214:217], v[76:79]
	v_mfma_f32_16x16x32_bf16 v[72:75], v[164:167], v[214:217], v[72:75]
	v_mfma_f32_16x16x32_bf16 v[116:119], v[168:171], v[184:187], v[116:119]
	v_mfma_f32_16x16x32_bf16 v[112:115], v[176:179], v[184:187], v[112:115]
	v_mfma_f32_16x16x32_bf16 v[100:103], v[168:171], v[192:195], v[100:103]
	v_mfma_f32_16x16x32_bf16 v[96:99], v[176:179], v[192:195], v[96:99]
	v_mfma_f32_16x16x32_bf16 v[84:87], v[168:171], v[200:203], v[84:87]
	v_mfma_f32_16x16x32_bf16 v[80:83], v[176:179], v[200:203], v[80:83]
	v_mfma_f32_16x16x32_bf16 v[68:71], v[168:171], v[210:213], v[68:71]
	v_mfma_f32_16x16x32_bf16 v[64:67], v[176:179], v[210:213], v[64:67]
	v_mfma_f32_16x16x32_bf16 v[116:119], v[172:175], v[188:191], v[116:119]
	v_mfma_f32_16x16x32_bf16 v[112:115], v[180:183], v[188:191], v[112:115]
	v_mfma_f32_16x16x32_bf16 v[100:103], v[172:175], v[196:199], v[100:103]
	v_mfma_f32_16x16x32_bf16 v[96:99], v[180:183], v[196:199], v[96:99]
	v_mfma_f32_16x16x32_bf16 v[84:87], v[172:175], v[206:209], v[84:87]
	v_mfma_f32_16x16x32_bf16 v[80:83], v[180:183], v[206:209], v[80:83]
	v_mfma_f32_16x16x32_bf16 v[68:71], v[172:175], v[214:217], v[68:71]
	v_mfma_f32_16x16x32_bf16 v[64:67], v[180:183], v[214:217], v[64:67]
	s_barrier
	ds_read_b128 v[184:187], v151 offset:16384
	ds_read_b128 v[188:191], v151 offset:17408
	ds_read_b128 v[192:195], v151 offset:18432
	ds_read_b128 v[196:199], v151 offset:19456
	ds_read_b128 v[200:203], v151 offset:20480
	ds_read_b128 v[206:209], v151 offset:21504
	ds_read_b128 v[210:213], v151 offset:22528
	ds_read_b128 v[214:217], v151 offset:23552
	s_add_i32 s51, s46, s35
	s_mov_b32 m0, s51
	v_lshl_add_u64 v[144:145], s[22:23], 0, v[132:133]
	global_load_lds_dwordx4 v[144:145], off
	s_add_i32 m0, s51, 0x2000
	s_add_u32 s52, s22, 0x80000
	v_lshl_add_u64 v[218:219], s[22:23], 0, v[128:129]
	s_addc_u32 s53, s23, 0
	s_add_i32 s51, s47, s35
	global_load_lds_dwordx4 v[218:219], off
	v_lshl_add_u64 v[220:221], s[52:53], 0, v[132:133]
	s_mov_b32 m0, s51
	v_lshl_add_u64 v[222:223], s[24:25], 0, v[130:131]
	global_load_lds_dwordx4 v[220:221], off
	v_lshl_add_u64 v[220:221], s[52:53], 0, v[128:129]
	s_add_i32 m0, s51, 0x2000
	s_nop 0
	global_load_lds_dwordx4 v[220:221], off
	v_lshl_add_u64 v[220:221], s[24:25], 0, v[134:135]
	s_mov_b32 m0, s19
	s_nop 0
	global_load_lds_dwordx4 v[220:221], off
	s_mov_b32 m0, s37
	s_nop 0
	global_load_lds_dwordx4 v[222:223], off
	s_waitcnt vmcnt(8)
	s_waitcnt lgkmcnt(0)
	s_barrier
; #define PG8_STAGE(bufoff, gbase, voff) do { _Pragma("unroll") for (int _i = 0; _i < 2; ++_i) \
;         __builtin_amdgcn_global_load_lds((const unsigned*)((const char*)(gbase) + (voff)[_i]), (PG8_LAS unsigned*)(lds + (bufoff) + ldsw + _i * 8192), 16, 0, 0); } while (0)
; #define PG8_LDA(dst, b, h) do { _Pragma("unroll") for (int m = 0; m < 4; ++m) _Pragma("unroll") for (int k = 0; k < 2; ++k) dst[m][k] = *(const PG8_LAS bf16x8*)(lds + PG8_SA(b, h) + aoff + m * 2048 + k * 1024); } while (0)
; #define PG8_LDB(dst, b, h) do { _Pragma("unroll") for (int n = 0; n < 2; ++n) _Pragma("unroll") for (int k = 0; k < 2; ++k) dst[n][k] = *(const PG8_LAS bf16x8*)(lds + PG8_SB(b, h) + boff + n * 2048 + k * 1024); } while (0)
; #define PG8_MMA(ai, bj, At, Bt) do { __builtin_amdgcn_s_setprio(1); _Pragma("unroll") for (int m = 0; m < 4; ++m) _Pragma("unroll") for (int n = 0; n < 2; ++n) _Pragma("unroll") for (int k = 0; k < 2; ++k) \
;         acc[ai][bj][m][n] = __builtin_amdgcn_mfma_f32_16x16x32_bf16(Bt[n][k], At[m][k], acc[ai][bj][m][n], 0, 0, 0); __builtin_amdgcn_s_setprio(0); } while (0)
; #define PG8_WAIT_V(n) asm volatile("s_waitcnt vmcnt(" #n ")" ::: "memory")
; #define PG8_WAIT_L(n) asm volatile("s_waitcnt lgkmcnt(" #n ")" ::: "memory")
; #define PG8_BAR __builtin_amdgcn_s_barrier()
; #define PG8_SCHED __builtin_amdgcn_sched_barrier(0)
; template <class Epi, class Sched, bool ALIGN_EPI = false, bool SP2 = false>
; __device__ __forceinline__ void gemm_phase(PG8_LAS unsigned char* lds, const Gemm g, const Sched& S, const Epi& E, const int wv0) {
;     ...
;             PG8_WAIT_V(8); PG8_WAIT_L(0); PG8_BAR; PG8_MMA(1, 0, At, B0); PG8_MMA(1, 1, At, B1); PG8_BAR; PG8_SCHED;
;             PG8_LDB(B0, 1, 0); PG8_LDB(B1, 1, 1); PG8_SCHED; PG8_LDA(At, 1, 0); PG8_STAGE(PG8_SA(0, 1), a2 + hstepA, voffA);
;             PG8_WAIT_V(8); PG8_WAIT_L(0); PG8_BAR; PG8_MMA(0, 0, At, B0); PG8_MMA(0, 1, At, B1); PG8_BAR; PG8_SCHED;
	v_mfma_f32_16x16x32_bf16 v[60:63], v[152:155], v[184:187], v[60:63]
	v_mfma_f32_16x16x32_bf16 v[56:59], v[160:163], v[184:187], v[56:59]
	v_mfma_f32_16x16x32_bf16 v[44:47], v[152:155], v[192:195], v[44:47]
	v_mfma_f32_16x16x32_bf16 v[40:43], v[160:163], v[192:195], v[40:43]
	v_mfma_f32_16x16x32_bf16 v[28:31], v[152:155], v[200:203], v[28:31]
	v_mfma_f32_16x16x32_bf16 v[24:27], v[160:163], v[200:203], v[24:27]
	v_mfma_f32_16x16x32_bf16 v[12:15], v[152:155], v[210:213], v[12:15]
	v_mfma_f32_16x16x32_bf16 v[8:11], v[160:163], v[210:213], v[8:11]
	v_mfma_f32_16x16x32_bf16 v[60:63], v[156:159], v[188:191], v[60:63]
	v_mfma_f32_16x16x32_bf16 v[56:59], v[164:167], v[188:191], v[56:59]
	v_mfma_f32_16x16x32_bf16 v[44:47], v[156:159], v[196:199], v[44:47]
	v_mfma_f32_16x16x32_bf16 v[40:43], v[164:167], v[196:199], v[40:43]
	v_mfma_f32_16x16x32_bf16 v[28:31], v[156:159], v[206:209], v[28:31]
	v_mfma_f32_16x16x32_bf16 v[24:27], v[164:167], v[206:209], v[24:27]
	v_mfma_f32_16x16x32_bf16 v[12:15], v[156:159], v[214:217], v[12:15]
	v_mfma_f32_16x16x32_bf16 v[8:11], v[164:167], v[214:217], v[8:11]
	v_mfma_f32_16x16x32_bf16 v[52:55], v[168:171], v[184:187], v[52:55]
	v_mfma_f32_16x16x32_bf16 v[48:51], v[176:179], v[184:187], v[48:51]
	v_mfma_f32_16x16x32_bf16 v[36:39], v[168:171], v[192:195], v[36:39]
	v_mfma_f32_16x16x32_bf16 v[32:35], v[176:179], v[192:195], v[32:35]
	v_mfma_f32_16x16x32_bf16 v[20:23], v[168:171], v[200:203], v[20:23]
	v_mfma_f32_16x16x32_bf16 v[16:19], v[176:179], v[200:203], v[16:19]
	v_mfma_f32_16x16x32_bf16 v[4:7], v[168:171], v[210:213], v[4:7]
	v_mfma_f32_16x16x32_bf16 v[0:3], v[176:179], v[210:213], v[0:3]
	v_mfma_f32_16x16x32_bf16 v[52:55], v[172:175], v[188:191], v[52:55]
	v_mfma_f32_16x16x32_bf16 v[48:51], v[180:183], v[188:191], v[48:51]
	v_mfma_f32_16x16x32_bf16 v[36:39], v[172:175], v[196:199], v[36:39]
	v_mfma_f32_16x16x32_bf16 v[32:35], v[180:183], v[196:199], v[32:35]
	v_mfma_f32_16x16x32_bf16 v[20:23], v[172:175], v[206:209], v[20:23]
	v_mfma_f32_16x16x32_bf16 v[16:19], v[180:183], v[206:209], v[16:19]
	v_mfma_f32_16x16x32_bf16 v[4:7], v[172:175], v[214:217], v[4:7]
	v_mfma_f32_16x16x32_bf16 v[0:3], v[180:183], v[214:217], v[0:3]
	s_barrier
	s_add_i32 s51, 0, 0x18000
	s_add_i32 s52, 0, 0x1c000
	v_add_u32_e32 v164, s51, v147
	v_add_u32_e32 v180, s52, v147
	ds_read_b128 v[152:155], v164
	ds_read_b128 v[156:159], v164 offset:1024
	ds_read_b128 v[160:163], v164 offset:2048
	ds_read_b128 v[164:167], v164 offset:3072
	ds_read_b128 v[168:171], v180
	ds_read_b128 v[172:175], v180 offset:1024
	ds_read_b128 v[176:179], v180 offset:2048
	ds_read_b128 v[180:183], v180 offset:3072
	s_add_u32 s24, s24, 0x80000
	s_addc_u32 s25, s25, 0
	s_mov_b32 m0, s38
	v_lshl_add_u64 v[224:225], s[24:25], 0, v[134:135]
	ds_read_b128 v[184:187], v151 offset:32768
	ds_read_b128 v[188:191], v151 offset:33792
	ds_read_b128 v[192:195], v151 offset:34816
	ds_read_b128 v[196:199], v151 offset:35840
	ds_read_b128 v[200:203], v151 offset:36864
	ds_read_b128 v[206:209], v151 offset:37888
	ds_read_b128 v[210:213], v151 offset:38912
	ds_read_b128 v[214:217], v151 offset:39936
	global_load_lds_dwordx4 v[224:225], off
	v_lshl_add_u64 v[224:225], s[24:25], 0, v[130:131]
	s_mov_b32 m0, s39
	s_nop 0
	global_load_lds_dwordx4 v[224:225], off
	s_waitcnt vmcnt(8)
	s_waitcnt lgkmcnt(0)
	s_barrier
	v_mfma_f32_16x16x32_bf16 v[124:127], v[152:155], v[184:187], v[124:127]
	v_mfma_f32_16x16x32_bf16 v[120:123], v[160:163], v[184:187], v[120:123]
	v_mfma_f32_16x16x32_bf16 v[108:111], v[152:155], v[192:195], v[108:111]
	v_mfma_f32_16x16x32_bf16 v[104:107], v[160:163], v[192:195], v[104:107]
	v_mfma_f32_16x16x32_bf16 v[92:95], v[152:155], v[200:203], v[92:95]
	v_mfma_f32_16x16x32_bf16 v[88:91], v[160:163], v[200:203], v[88:91]
	v_mfma_f32_16x16x32_bf16 v[76:79], v[152:155], v[210:213], v[76:79]
	v_mfma_f32_16x16x32_bf16 v[72:75], v[160:163], v[210:213], v[72:75]
	v_mfma_f32_16x16x32_bf16 v[124:127], v[156:159], v[188:191], v[124:127]
	v_mfma_f32_16x16x32_bf16 v[120:123], v[164:167], v[188:191], v[120:123]
	v_mfma_f32_16x16x32_bf16 v[108:111], v[156:159], v[196:199], v[108:111]
	v_mfma_f32_16x16x32_bf16 v[104:107], v[164:167], v[196:199], v[104:107]
	v_mfma_f32_16x16x32_bf16 v[92:95], v[156:159], v[206:209], v[92:95]
	v_mfma_f32_16x16x32_bf16 v[88:91], v[164:167], v[206:209], v[88:91]
	v_mfma_f32_16x16x32_bf16 v[76:79], v[156:159], v[214:217], v[76:79]
	v_mfma_f32_16x16x32_bf16 v[72:75], v[164:167], v[214:217], v[72:75]
	v_mfma_f32_16x16x32_bf16 v[116:119], v[168:171], v[184:187], v[116:119]
	v_mfma_f32_16x16x32_bf16 v[112:115], v[176:179], v[184:187], v[112:115]
	v_mfma_f32_16x16x32_bf16 v[100:103], v[168:171], v[192:195], v[100:103]
	v_mfma_f32_16x16x32_bf16 v[96:99], v[176:179], v[192:195], v[96:99]
	v_mfma_f32_16x16x32_bf16 v[84:87], v[168:171], v[200:203], v[84:87]
	v_mfma_f32_16x16x32_bf16 v[80:83], v[176:179], v[200:203], v[80:83]
	v_mfma_f32_16x16x32_bf16 v[68:71], v[168:171], v[210:213], v[68:71]
	v_mfma_f32_16x16x32_bf16 v[64:67], v[176:179], v[210:213], v[64:67]
	v_mfma_f32_16x16x32_bf16 v[116:119], v[172:175], v[188:191], v[116:119]
	v_mfma_f32_16x16x32_bf16 v[112:115], v[180:183], v[188:191], v[112:115]
	v_mfma_f32_16x16x32_bf16 v[100:103], v[172:175], v[196:199], v[100:103]
	v_mfma_f32_16x16x32_bf16 v[96:99], v[180:183], v[196:199], v[96:99]
	v_mfma_f32_16x16x32_bf16 v[84:87], v[172:175], v[206:209], v[84:87]
	v_mfma_f32_16x16x32_bf16 v[80:83], v[180:183], v[206:209], v[80:83]
	v_mfma_f32_16x16x32_bf16 v[68:71], v[172:175], v[214:217], v[68:71]
	v_mfma_f32_16x16x32_bf16 v[64:67], v[180:183], v[214:217], v[64:67]
	s_barrier
; #define PG8_STAGE(bufoff, gbase, voff) do { _Pragma("unroll") for (int _i = 0; _i < 2; ++_i) \
;         __builtin_amdgcn_global_load_lds((const unsigned*)((const char*)(gbase) + (voff)[_i]), (PG8_LAS unsigned*)(lds + (bufoff) + ldsw + _i * 8192), 16, 0, 0); } while (0)
; #define PG8_LDA(dst, b, h) do { _Pragma("unroll") for (int m = 0; m < 4; ++m) _Pragma("unroll") for (int k = 0; k < 2; ++k) dst[m][k] = *(const PG8_LAS bf16x8*)(lds + PG8_SA(b, h) + aoff + m * 2048 + k * 1024); } while (0)
; #define PG8_MMA(ai, bj, At, Bt) do { __builtin_amdgcn_s_setprio(1); _Pragma("unroll") for (int m = 0; m < 4; ++m) _Pragma("unroll") for (int n = 0; n < 2; ++n) _Pragma("unroll") for (int k = 0; k < 2; ++k) \
;         acc[ai][bj][m][n] = __builtin_amdgcn_mfma_f32_16x16x32_bf16(Bt[n][k], At[m][k], acc[ai][bj][m][n], 0, 0, 0); __builtin_amdgcn_s_setprio(0); } while (0)
; #define PG8_WAIT_V(n) asm volatile("s_waitcnt vmcnt(" #n ")" ::: "memory")
; #define PG8_WAIT_L(n) asm volatile("s_waitcnt lgkmcnt(" #n ")" ::: "memory")
; #define PG8_BAR __builtin_amdgcn_s_barrier()
; #define PG8_SCHED __builtin_amdgcn_sched_barrier(0)
; template <class Epi, class Sched, bool ALIGN_EPI = false, bool SP2 = false>
; __device__ __forceinline__ void gemm_phase(PG8_LAS unsigned char* lds, const Gemm g, const Sched& S, const Epi& E, const int wv0) {
;     ...
;             PG8_LDA(At, 1, 1); PG8_STAGE(PG8_SB(1, 0), b3, voffB); PG8_STAGE(PG8_SB(1, 1), b3 + hstepB, voffB); PG8_STAGE(PG8_SA(1, 0), a3, voffA);
;             PG8_WAIT_V(8); PG8_WAIT_L(0); PG8_BAR; PG8_MMA(1, 0, At, B0); PG8_MMA(1, 1, At, B1); PG8_BAR; PG8_SCHED;
;     ...
;         if constexpr (ALIGN_EPI) { if (wr == 0) PG8_BAR; }
	ds_read_b128 v[184:187], v151 offset:49152
	ds_read_b128 v[188:191], v151 offset:50176
	ds_read_b128 v[192:195], v151 offset:51200
	ds_read_b128 v[196:199], v151 offset:52224
	ds_read_b128 v[200:203], v151 offset:53248
	ds_read_b128 v[206:209], v151 offset:54272
	ds_read_b128 v[210:213], v151 offset:55296
	ds_read_b128 v[214:217], v151 offset:56320
	s_add_i32 s24, s51, s35
	s_mov_b32 m0, s24
	v_lshl_add_u64 v[144:145], v[144:145], 0, s[6:7]
	global_load_lds_dwordx4 v[144:145], off
	s_add_i32 m0, s24, 0x2000
	s_add_u32 s22, s22, 0x80080
	v_lshl_add_u64 v[144:145], v[218:219], 0, s[6:7]
	s_addc_u32 s23, s23, 0
	s_add_i32 s24, s52, s35
	global_load_lds_dwordx4 v[144:145], off
	v_lshl_add_u64 v[144:145], s[22:23], 0, v[132:133]
	s_mov_b32 m0, s24
	s_nop 0
	global_load_lds_dwordx4 v[144:145], off
	v_lshl_add_u64 v[144:145], s[22:23], 0, v[128:129]
	s_add_i32 m0, s24, 0x2000
	s_nop 0
	global_load_lds_dwordx4 v[144:145], off
	v_lshl_add_u64 v[144:145], v[220:221], 0, s[6:7]
	s_mov_b32 m0, s41
	s_nop 0
	global_load_lds_dwordx4 v[144:145], off
	v_lshl_add_u64 v[144:145], v[222:223], 0, s[6:7]
	s_mov_b32 m0, s44
	s_nop 0
	global_load_lds_dwordx4 v[144:145], off
	s_waitcnt vmcnt(8)
	s_waitcnt lgkmcnt(0)
	s_barrier
	v_mfma_f32_16x16x32_bf16 v[60:63], v[152:155], v[184:187], v[60:63]
	v_mfma_f32_16x16x32_bf16 v[56:59], v[160:163], v[184:187], v[56:59]
	v_mfma_f32_16x16x32_bf16 v[44:47], v[152:155], v[192:195], v[44:47]
	v_mfma_f32_16x16x32_bf16 v[40:43], v[160:163], v[192:195], v[40:43]
	v_mfma_f32_16x16x32_bf16 v[28:31], v[152:155], v[200:203], v[28:31]
	v_mfma_f32_16x16x32_bf16 v[24:27], v[160:163], v[200:203], v[24:27]
	v_mfma_f32_16x16x32_bf16 v[12:15], v[152:155], v[210:213], v[12:15]
	v_mfma_f32_16x16x32_bf16 v[8:11], v[160:163], v[210:213], v[8:11]
	v_mfma_f32_16x16x32_bf16 v[60:63], v[156:159], v[188:191], v[60:63]
	v_mfma_f32_16x16x32_bf16 v[56:59], v[164:167], v[188:191], v[56:59]
	v_mfma_f32_16x16x32_bf16 v[44:47], v[156:159], v[196:199], v[44:47]
	v_mfma_f32_16x16x32_bf16 v[40:43], v[164:167], v[196:199], v[40:43]
	v_mfma_f32_16x16x32_bf16 v[28:31], v[156:159], v[206:209], v[28:31]
	v_mfma_f32_16x16x32_bf16 v[24:27], v[164:167], v[206:209], v[24:27]
	v_mfma_f32_16x16x32_bf16 v[12:15], v[156:159], v[214:217], v[12:15]
	v_mfma_f32_16x16x32_bf16 v[8:11], v[164:167], v[214:217], v[8:11]
	v_mfma_f32_16x16x32_bf16 v[52:55], v[168:171], v[184:187], v[52:55]
	v_mfma_f32_16x16x32_bf16 v[48:51], v[176:179], v[184:187], v[48:51]
	v_mfma_f32_16x16x32_bf16 v[36:39], v[168:171], v[192:195], v[36:39]
	v_mfma_f32_16x16x32_bf16 v[32:35], v[176:179], v[192:195], v[32:35]
	v_mfma_f32_16x16x32_bf16 v[20:23], v[168:171], v[200:203], v[20:23]
	v_mfma_f32_16x16x32_bf16 v[16:19], v[176:179], v[200:203], v[16:19]
	v_mfma_f32_16x16x32_bf16 v[4:7], v[168:171], v[210:213], v[4:7]
	v_mfma_f32_16x16x32_bf16 v[0:3], v[176:179], v[210:213], v[0:3]
	v_mfma_f32_16x16x32_bf16 v[52:55], v[172:175], v[188:191], v[52:55]
	v_mfma_f32_16x16x32_bf16 v[48:51], v[180:183], v[188:191], v[48:51]
	v_mfma_f32_16x16x32_bf16 v[36:39], v[172:175], v[196:199], v[36:39]
	v_mfma_f32_16x16x32_bf16 v[32:35], v[180:183], v[196:199], v[32:35]
	v_mfma_f32_16x16x32_bf16 v[20:23], v[172:175], v[206:209], v[20:23]
	v_mfma_f32_16x16x32_bf16 v[16:19], v[180:183], v[206:209], v[16:19]
	v_mfma_f32_16x16x32_bf16 v[4:7], v[172:175], v[214:217], v[4:7]
	v_mfma_f32_16x16x32_bf16 v[0:3], v[180:183], v[214:217], v[0:3]
	s_barrier
	s_add_i32 s50, s50, 2
	s_add_u32 s11, s11, 0x100
	s_addc_u32 s13, s13, 0
	s_add_u32 s20, s20, 0x100
	s_addc_u32 s21, s21, 0
	s_cmp_gt_u32 s50, 29
	s_cbranch_scc0 .LBB0_790
	s_and_b64 vcc, exec, s[8:9]
	s_cbranch_vccz .LBB0_793
	s_barrier

; #define PG8_STAGE(bufoff, gbase, voff) do { _Pragma("unroll") for (int _i = 0; _i < 2; ++_i) \
;         __builtin_amdgcn_global_load_lds((const unsigned*)((const char*)(gbase) + (voff)[_i]), (PG8_LAS unsigned*)(lds + (bufoff) + ldsw + _i * 8192), 16, 0, 0); } while (0)
; #define PG8_LDA(dst, b, h) do { _Pragma("unroll") for (int m = 0; m < 4; ++m) _Pragma("unroll") for (int k = 0; k < 2; ++k) dst[m][k] = *(const PG8_LAS bf16x8*)(lds + PG8_SA(b, h) + aoff + m * 2048 + k * 1024); } while (0)
; #define PG8_LDB(dst, b, h) do { _Pragma("unroll") for (int n = 0; n < 2; ++n) _Pragma("unroll") for (int k = 0; k < 2; ++k) dst[n][k] = *(const PG8_LAS bf16x8*)(lds + PG8_SB(b, h) + boff + n * 2048 + k * 1024); } while (0)
; #define PG8_MMA(ai, bj, At, Bt) do { __builtin_amdgcn_s_setprio(1); _Pragma("unroll") for (int m = 0; m < 4; ++m) _Pragma("unroll") for (int n = 0; n < 2; ++n) _Pragma("unroll") for (int k = 0; k < 2; ++k) \
;         acc[ai][bj][m][n] = __builtin_amdgcn_mfma_f32_16x16x32_bf16(Bt[n][k], At[m][k], acc[ai][bj][m][n], 0, 0, 0); __builtin_amdgcn_s_setprio(0); } while (0)
; #define PG8_WAIT_V(n) asm volatile("s_waitcnt vmcnt(" #n ")" ::: "memory")
; #define PG8_WAIT_L(n) asm volatile("s_waitcnt lgkmcnt(" #n ")" ::: "memory")
; template <class Epi, class Sched, bool ALIGN_EPI = false, bool SP2 = false>
; __device__ __forceinline__ void gemm_phase(PG8_LAS unsigned char* lds, const Gemm g, const Sched& S, const Epi& E, const int wv0) {
;     ...
;         for (int t = 0; t < nt; t += 2) {
;             const bool last = (t == nt - 2);
;             const char* a1 = cA + (size_t)(t + 1) * kstep;
;             const char* a2 = last ? nA : cA + (size_t)(t + 2) * kstep; const char* b2 = last ? nB : cB + (size_t)(t + 2) * kstep;
;             const char* a3 = a2 + kstep; const char* b3 = b2 + kstep;
;             if constexpr (SP2) {
;             PG8_LDB(B0, 0, 0); PG8_LDB(B1, 0, 1); PG8_SCHED; PG8_LDA(At, 0, 0); PG8_STAGE(PG8_SA(1, 1), a1 + hstepA, voffA);
;             PG8_WAIT_V(8); PG8_WAIT_L(0); PG8_BAR; PG8_MMA(0, 0, At, B0); PG8_MMA(0, 1, At, B1); PG8_BAR; PG8_SCHED;
;             PG8_LDA(At, 0, 1); PG8_STAGE(PG8_SB(0, 0), b2, voffB); PG8_STAGE(PG8_SB(0, 1), b2 + hstepB, voffB); PG8_STAGE(PG8_SA(0, 0), a2, voffA);
;             PG8_WAIT_V(8); PG8_WAIT_L(0); PG8_BAR; PG8_MMA(1, 0, At, B0); PG8_MMA(1, 1, At, B1); PG8_BAR; PG8_SCHED;
.LBB0_867:
	ds_read_b128 v[144:147], v155
	ds_read_b128 v[148:151], v155 offset:1024
	ds_read_b128 v[158:161], v155 offset:2048
	ds_read_b128 v[162:165], v155 offset:3072
	ds_read_b128 v[166:169], v156
	ds_read_b128 v[170:173], v156 offset:1024
	ds_read_b128 v[174:177], v156 offset:2048
	ds_read_b128 v[178:181], v156 offset:3072
	ds_read_b128 v[182:185], v157
	ds_read_b128 v[186:189], v157 offset:1024
	ds_read_b128 v[190:193], v157 offset:2048
	ds_read_b128 v[194:197], v157 offset:3072
	ds_read_b128 v[198:201], v157 offset:4096
	ds_read_b128 v[206:209], v157 offset:5120
	ds_read_b128 v[210:213], v157 offset:6144
	ds_read_b128 v[214:217], v157 offset:7168
	s_add_u32 s24, s22, 0x100
	s_addc_u32 s25, s23, 0
	s_cmpk_eq_i32 s58, 0x54
	s_cselect_b32 s29, s19, s25
	s_cselect_b32 s28, s18, s24
	s_cselect_b32 s27, s21, s57
	s_cselect_b32 s26, s20, s56
	s_add_i32 m0, s40, 0xc000
	v_lshl_add_u64 v[202:203], s[22:23], 0, v[138:139]
	global_load_lds_dwordx4 v[202:203], off
	v_lshl_add_u64 v[202:203], s[22:23], 0, v[136:137]
	s_add_i32 m0, s40, 0xe000
	s_nop 0
	global_load_lds_dwordx4 v[202:203], off
	s_waitcnt vmcnt(8)
	s_waitcnt lgkmcnt(0)
	s_barrier
	v_mfma_f32_16x16x32_bf16 v[124:127], v[144:147], v[182:185], v[124:127]
	v_mfma_f32_16x16x32_bf16 v[120:123], v[158:161], v[182:185], v[120:123]
	v_mfma_f32_16x16x32_bf16 v[116:119], v[144:147], v[190:193], v[116:119]
	v_mfma_f32_16x16x32_bf16 v[112:115], v[158:161], v[190:193], v[112:115]
	v_mfma_f32_16x16x32_bf16 v[92:95], v[144:147], v[198:201], v[92:95]
	v_mfma_f32_16x16x32_bf16 v[88:91], v[158:161], v[198:201], v[88:91]
	v_mfma_f32_16x16x32_bf16 v[84:87], v[144:147], v[210:213], v[84:87]
	v_mfma_f32_16x16x32_bf16 v[80:83], v[158:161], v[210:213], v[80:83]
	v_mfma_f32_16x16x32_bf16 v[124:127], v[148:151], v[186:189], v[124:127]
	v_mfma_f32_16x16x32_bf16 v[120:123], v[162:165], v[186:189], v[120:123]
	v_mfma_f32_16x16x32_bf16 v[116:119], v[148:151], v[194:197], v[116:119]
	v_mfma_f32_16x16x32_bf16 v[112:115], v[162:165], v[194:197], v[112:115]
	v_mfma_f32_16x16x32_bf16 v[92:95], v[148:151], v[206:209], v[92:95]
	v_mfma_f32_16x16x32_bf16 v[88:91], v[162:165], v[206:209], v[88:91]
	v_mfma_f32_16x16x32_bf16 v[84:87], v[148:151], v[214:217], v[84:87]
	v_mfma_f32_16x16x32_bf16 v[80:83], v[162:165], v[214:217], v[80:83]
	v_mfma_f32_16x16x32_bf16 v[108:111], v[166:169], v[182:185], v[108:111]
	v_mfma_f32_16x16x32_bf16 v[104:107], v[174:177], v[182:185], v[104:107]
	v_mfma_f32_16x16x32_bf16 v[100:103], v[166:169], v[190:193], v[100:103]
	v_mfma_f32_16x16x32_bf16 v[96:99], v[174:177], v[190:193], v[96:99]
	v_mfma_f32_16x16x32_bf16 v[76:79], v[166:169], v[198:201], v[76:79]
	v_mfma_f32_16x16x32_bf16 v[72:75], v[174:177], v[198:201], v[72:75]
	v_mfma_f32_16x16x32_bf16 v[68:71], v[166:169], v[210:213], v[68:71]
	v_mfma_f32_16x16x32_bf16 v[64:67], v[174:177], v[210:213], v[64:67]
	v_mfma_f32_16x16x32_bf16 v[108:111], v[170:173], v[186:189], v[108:111]
	v_mfma_f32_16x16x32_bf16 v[104:107], v[178:181], v[186:189], v[104:107]
	v_mfma_f32_16x16x32_bf16 v[100:103], v[170:173], v[194:197], v[100:103]
	v_mfma_f32_16x16x32_bf16 v[96:99], v[178:181], v[194:197], v[96:99]
	v_mfma_f32_16x16x32_bf16 v[76:79], v[170:173], v[206:209], v[76:79]
	v_mfma_f32_16x16x32_bf16 v[72:75], v[178:181], v[206:209], v[72:75]
	v_mfma_f32_16x16x32_bf16 v[68:71], v[170:173], v[214:217], v[68:71]
	v_mfma_f32_16x16x32_bf16 v[64:67], v[178:181], v[214:217], v[64:67]
	s_barrier
	ds_read_b128 v[182:185], v157 offset:16384
	ds_read_b128 v[186:189], v157 offset:17408
	ds_read_b128 v[190:193], v157 offset:18432
	ds_read_b128 v[194:197], v157 offset:19456
	ds_read_b128 v[198:201], v157 offset:20480
	ds_read_b128 v[206:209], v157 offset:21504
	ds_read_b128 v[210:213], v157 offset:22528
	ds_read_b128 v[214:217], v157 offset:23552
	s_add_i32 s22, s50, s39
	s_mov_b32 m0, s22
	v_lshl_add_u64 v[202:203], s[26:27], 0, v[130:131]
	global_load_lds_dwordx4 v[202:203], off
	s_add_i32 m0, s22, 0x2000
	s_add_u32 s22, s26, 0x160000
	v_lshl_add_u64 v[218:219], s[26:27], 0, v[134:135]
	s_addc_u32 s23, s27, 0
	s_add_i32 s59, s51, s39
	global_load_lds_dwordx4 v[218:219], off
	v_lshl_add_u64 v[220:221], s[22:23], 0, v[130:131]
	s_mov_b32 m0, s59
	v_lshl_add_u64 v[222:223], s[28:29], 0, v[132:133]
	global_load_lds_dwordx4 v[220:221], off
	v_lshl_add_u64 v[220:221], s[22:23], 0, v[134:135]
	s_add_i32 m0, s59, 0x2000
	s_nop 0
	global_load_lds_dwordx4 v[220:221], off
	v_lshl_add_u64 v[220:221], s[28:29], 0, v[128:129]
	s_mov_b32 m0, s40
	s_nop 0
	global_load_lds_dwordx4 v[220:221], off
	s_mov_b32 m0, s41
	s_nop 0
	global_load_lds_dwordx4 v[222:223], off
	s_waitcnt vmcnt(8)
	s_waitcnt lgkmcnt(0)
	s_barrier
; #define PG8_STAGE(bufoff, gbase, voff) do { _Pragma("unroll") for (int _i = 0; _i < 2; ++_i) \
;         __builtin_amdgcn_global_load_lds((const unsigned*)((const char*)(gbase) + (voff)[_i]), (PG8_LAS unsigned*)(lds + (bufoff) + ldsw + _i * 8192), 16, 0, 0); } while (0)
; #define PG8_LDA(dst, b, h) do { _Pragma("unroll") for (int m = 0; m < 4; ++m) _Pragma("unroll") for (int k = 0; k < 2; ++k) dst[m][k] = *(const PG8_LAS bf16x8*)(lds + PG8_SA(b, h) + aoff + m * 2048 + k * 1024); } while (0)
; #define PG8_LDB(dst, b, h) do { _Pragma("unroll") for (int n = 0; n < 2; ++n) _Pragma("unroll") for (int k = 0; k < 2; ++k) dst[n][k] = *(const PG8_LAS bf16x8*)(lds + PG8_SB(b, h) + boff + n * 2048 + k * 1024); } while (0)
; #define PG8_MMA(ai, bj, At, Bt) do { __builtin_amdgcn_s_setprio(1); _Pragma("unroll") for (int m = 0; m < 4; ++m) _Pragma("unroll") for (int n = 0; n < 2; ++n) _Pragma("unroll") for (int k = 0; k < 2; ++k) \
;         acc[ai][bj][m][n] = __builtin_amdgcn_mfma_f32_16x16x32_bf16(Bt[n][k], At[m][k], acc[ai][bj][m][n], 0, 0, 0); __builtin_amdgcn_s_setprio(0); } while (0)
; #define PG8_WAIT_V(n) asm volatile("s_waitcnt vmcnt(" #n ")" ::: "memory")
; #define PG8_WAIT_L(n) asm volatile("s_waitcnt lgkmcnt(" #n ")" ::: "memory")
; #define PG8_BAR __builtin_amdgcn_s_barrier()
; #define PG8_SCHED __builtin_amdgcn_sched_barrier(0)
; template <class Epi, class Sched, bool ALIGN_EPI = false, bool SP2 = false>
; __device__ __forceinline__ void gemm_phase(PG8_LAS unsigned char* lds, const Gemm g, const Sched& S, const Epi& E, const int wv0) {
;     ...
;             PG8_WAIT_V(8); PG8_WAIT_L(0); PG8_BAR; PG8_MMA(1, 0, At, B0); PG8_MMA(1, 1, At, B1); PG8_BAR; PG8_SCHED;
;             PG8_LDB(B0, 1, 0); PG8_LDB(B1, 1, 1); PG8_SCHED; PG8_LDA(At, 1, 0); PG8_STAGE(PG8_SA(0, 1), a2 + hstepA, voffA);
;             PG8_WAIT_V(8); PG8_WAIT_L(0); PG8_BAR; PG8_MMA(0, 0, At, B0); PG8_MMA(0, 1, At, B1); PG8_BAR; PG8_SCHED;
	v_mfma_f32_16x16x32_bf16 v[60:63], v[144:147], v[182:185], v[60:63]
	v_mfma_f32_16x16x32_bf16 v[56:59], v[158:161], v[182:185], v[56:59]
	v_mfma_f32_16x16x32_bf16 v[52:55], v[144:147], v[190:193], v[52:55]
	v_mfma_f32_16x16x32_bf16 v[48:51], v[158:161], v[190:193], v[48:51]
	v_mfma_f32_16x16x32_bf16 v[28:31], v[144:147], v[198:201], v[28:31]
	v_mfma_f32_16x16x32_bf16 v[24:27], v[158:161], v[198:201], v[24:27]
	v_mfma_f32_16x16x32_bf16 v[20:23], v[144:147], v[210:213], v[20:23]
	v_mfma_f32_16x16x32_bf16 v[16:19], v[158:161], v[210:213], v[16:19]
	v_mfma_f32_16x16x32_bf16 v[60:63], v[148:151], v[186:189], v[60:63]
	v_mfma_f32_16x16x32_bf16 v[56:59], v[162:165], v[186:189], v[56:59]
	v_mfma_f32_16x16x32_bf16 v[52:55], v[148:151], v[194:197], v[52:55]
	v_mfma_f32_16x16x32_bf16 v[48:51], v[162:165], v[194:197], v[48:51]
	v_mfma_f32_16x16x32_bf16 v[28:31], v[148:151], v[206:209], v[28:31]
	v_mfma_f32_16x16x32_bf16 v[24:27], v[162:165], v[206:209], v[24:27]
	v_mfma_f32_16x16x32_bf16 v[20:23], v[148:151], v[214:217], v[20:23]
	v_mfma_f32_16x16x32_bf16 v[16:19], v[162:165], v[214:217], v[16:19]
	v_mfma_f32_16x16x32_bf16 v[44:47], v[166:169], v[182:185], v[44:47]
	v_mfma_f32_16x16x32_bf16 v[40:43], v[174:177], v[182:185], v[40:43]
	v_mfma_f32_16x16x32_bf16 v[36:39], v[166:169], v[190:193], v[36:39]
	v_mfma_f32_16x16x32_bf16 v[32:35], v[174:177], v[190:193], v[32:35]
	v_mfma_f32_16x16x32_bf16 v[12:15], v[166:169], v[198:201], v[12:15]
	v_mfma_f32_16x16x32_bf16 v[8:11], v[174:177], v[198:201], v[8:11]
	v_mfma_f32_16x16x32_bf16 v[4:7], v[166:169], v[210:213], v[4:7]
	v_mfma_f32_16x16x32_bf16 v[0:3], v[174:177], v[210:213], v[0:3]
	v_mfma_f32_16x16x32_bf16 v[44:47], v[170:173], v[186:189], v[44:47]
	v_mfma_f32_16x16x32_bf16 v[40:43], v[178:181], v[186:189], v[40:43]
	v_mfma_f32_16x16x32_bf16 v[36:39], v[170:173], v[194:197], v[36:39]
	v_mfma_f32_16x16x32_bf16 v[32:35], v[178:181], v[194:197], v[32:35]
	v_mfma_f32_16x16x32_bf16 v[12:15], v[170:173], v[206:209], v[12:15]
	v_mfma_f32_16x16x32_bf16 v[8:11], v[178:181], v[206:209], v[8:11]
	v_mfma_f32_16x16x32_bf16 v[4:7], v[170:173], v[214:217], v[4:7]
	v_mfma_f32_16x16x32_bf16 v[0:3], v[178:181], v[214:217], v[0:3]
	s_barrier
	s_add_i32 s59, 0, 0x18000
	s_add_i32 s60, 0, 0x1c000
	v_add_u32_e32 v162, s59, v153
	v_add_u32_e32 v178, s60, v153
	ds_read_b128 v[144:147], v162
	ds_read_b128 v[148:151], v162 offset:1024
	ds_read_b128 v[158:161], v162 offset:2048
	ds_read_b128 v[162:165], v162 offset:3072
	ds_read_b128 v[166:169], v178
	ds_read_b128 v[170:173], v178 offset:1024
	ds_read_b128 v[174:177], v178 offset:2048
	ds_read_b128 v[178:181], v178 offset:3072
	s_add_u32 s22, s28, 0x160000
	s_addc_u32 s23, s29, 0
	s_mov_b32 m0, s44
	v_lshl_add_u64 v[224:225], s[22:23], 0, v[128:129]
	ds_read_b128 v[182:185], v157 offset:32768
	ds_read_b128 v[186:189], v157 offset:33792
	ds_read_b128 v[190:193], v157 offset:34816
	ds_read_b128 v[194:197], v157 offset:35840
	ds_read_b128 v[198:201], v157 offset:36864
	ds_read_b128 v[206:209], v157 offset:37888
	ds_read_b128 v[210:213], v157 offset:38912
	ds_read_b128 v[214:217], v157 offset:39936
	global_load_lds_dwordx4 v[224:225], off
	v_lshl_add_u64 v[224:225], s[22:23], 0, v[132:133]
	s_mov_b32 m0, s45
	s_nop 0
	global_load_lds_dwordx4 v[224:225], off
	s_waitcnt vmcnt(8)
	s_waitcnt lgkmcnt(0)
	s_barrier
	v_mfma_f32_16x16x32_bf16 v[124:127], v[144:147], v[182:185], v[124:127]
	v_mfma_f32_16x16x32_bf16 v[120:123], v[158:161], v[182:185], v[120:123]
	v_mfma_f32_16x16x32_bf16 v[116:119], v[144:147], v[190:193], v[116:119]
	v_mfma_f32_16x16x32_bf16 v[112:115], v[158:161], v[190:193], v[112:115]
	v_mfma_f32_16x16x32_bf16 v[92:95], v[144:147], v[198:201], v[92:95]
	v_mfma_f32_16x16x32_bf16 v[88:91], v[158:161], v[198:201], v[88:91]
	v_mfma_f32_16x16x32_bf16 v[84:87], v[144:147], v[210:213], v[84:87]
	v_mfma_f32_16x16x32_bf16 v[80:83], v[158:161], v[210:213], v[80:83]
	v_mfma_f32_16x16x32_bf16 v[124:127], v[148:151], v[186:189], v[124:127]
	v_mfma_f32_16x16x32_bf16 v[120:123], v[162:165], v[186:189], v[120:123]
	v_mfma_f32_16x16x32_bf16 v[116:119], v[148:151], v[194:197], v[116:119]
	v_mfma_f32_16x16x32_bf16 v[112:115], v[162:165], v[194:197], v[112:115]
	v_mfma_f32_16x16x32_bf16 v[92:95], v[148:151], v[206:209], v[92:95]
	v_mfma_f32_16x16x32_bf16 v[88:91], v[162:165], v[206:209], v[88:91]
	v_mfma_f32_16x16x32_bf16 v[84:87], v[148:151], v[214:217], v[84:87]
	v_mfma_f32_16x16x32_bf16 v[80:83], v[162:165], v[214:217], v[80:83]
	v_mfma_f32_16x16x32_bf16 v[108:111], v[166:169], v[182:185], v[108:111]
	v_mfma_f32_16x16x32_bf16 v[104:107], v[174:177], v[182:185], v[104:107]
	v_mfma_f32_16x16x32_bf16 v[100:103], v[166:169], v[190:193], v[100:103]
	v_mfma_f32_16x16x32_bf16 v[96:99], v[174:177], v[190:193], v[96:99]
	v_mfma_f32_16x16x32_bf16 v[76:79], v[166:169], v[198:201], v[76:79]
	v_mfma_f32_16x16x32_bf16 v[72:75], v[174:177], v[198:201], v[72:75]
	v_mfma_f32_16x16x32_bf16 v[68:71], v[166:169], v[210:213], v[68:71]
	v_mfma_f32_16x16x32_bf16 v[64:67], v[174:177], v[210:213], v[64:67]
	v_mfma_f32_16x16x32_bf16 v[108:111], v[170:173], v[186:189], v[108:111]
	v_mfma_f32_16x16x32_bf16 v[104:107], v[178:181], v[186:189], v[104:107]
	v_mfma_f32_16x16x32_bf16 v[100:103], v[170:173], v[194:197], v[100:103]
	v_mfma_f32_16x16x32_bf16 v[96:99], v[178:181], v[194:197], v[96:99]
	v_mfma_f32_16x16x32_bf16 v[76:79], v[170:173], v[206:209], v[76:79]
	v_mfma_f32_16x16x32_bf16 v[72:75], v[178:181], v[206:209], v[72:75]
	v_mfma_f32_16x16x32_bf16 v[68:71], v[170:173], v[214:217], v[68:71]
	v_mfma_f32_16x16x32_bf16 v[64:67], v[178:181], v[214:217], v[64:67]
	s_barrier
; #define PG8_STAGE(bufoff, gbase, voff) do { _Pragma("unroll") for (int _i = 0; _i < 2; ++_i) \
;         __builtin_amdgcn_global_load_lds((const unsigned*)((const char*)(gbase) + (voff)[_i]), (PG8_LAS unsigned*)(lds + (bufoff) + ldsw + _i * 8192), 16, 0, 0); } while (0)
; #define PG8_LDA(dst, b, h) do { _Pragma("unroll") for (int m = 0; m < 4; ++m) _Pragma("unroll") for (int k = 0; k < 2; ++k) dst[m][k] = *(const PG8_LAS bf16x8*)(lds + PG8_SA(b, h) + aoff + m * 2048 + k * 1024); } while (0)
; #define PG8_MMA(ai, bj, At, Bt) do { __builtin_amdgcn_s_setprio(1); _Pragma("unroll") for (int m = 0; m < 4; ++m) _Pragma("unroll") for (int n = 0; n < 2; ++n) _Pragma("unroll") for (int k = 0; k < 2; ++k) \
;         acc[ai][bj][m][n] = __builtin_amdgcn_mfma_f32_16x16x32_bf16(Bt[n][k], At[m][k], acc[ai][bj][m][n], 0, 0, 0); __builtin_amdgcn_s_setprio(0); } while (0)
; #define PG8_WAIT_V(n) asm volatile("s_waitcnt vmcnt(" #n ")" ::: "memory")
; #define PG8_WAIT_L(n) asm volatile("s_waitcnt lgkmcnt(" #n ")" ::: "memory")
; #define PG8_BAR __builtin_amdgcn_s_barrier()
; #define PG8_SCHED __builtin_amdgcn_sched_barrier(0)
; template <class Epi, class Sched, bool ALIGN_EPI = false, bool SP2 = false>
; __device__ __forceinline__ void gemm_phase(PG8_LAS unsigned char* lds, const Gemm g, const Sched& S, const Epi& E, const int wv0) {
;     ...
;             PG8_LDA(At, 1, 1); PG8_STAGE(PG8_SB(1, 0), b3, voffB); PG8_STAGE(PG8_SB(1, 1), b3 + hstepB, voffB); PG8_STAGE(PG8_SA(1, 0), a3, voffA);
;             PG8_WAIT_V(8); PG8_WAIT_L(0); PG8_BAR; PG8_MMA(1, 0, At, B0); PG8_MMA(1, 1, At, B1); PG8_BAR; PG8_SCHED;
	s_add_i32 s22, s59, s39
	v_lshl_add_u64 v[202:203], v[202:203], 0, s[6:7]
	s_mov_b32 m0, s22
	ds_read_b128 v[182:185], v157 offset:49152
	ds_read_b128 v[186:189], v157 offset:50176
	ds_read_b128 v[190:193], v157 offset:51200
	ds_read_b128 v[194:197], v157 offset:52224
	ds_read_b128 v[198:201], v157 offset:53248
	ds_read_b128 v[206:209], v157 offset:54272
	ds_read_b128 v[210:213], v157 offset:55296
	ds_read_b128 v[214:217], v157 offset:56320
	global_load_lds_dwordx4 v[202:203], off
	s_add_i32 m0, s22, 0x2000
	s_add_u32 s22, s26, 0x160080
	v_lshl_add_u64 v[202:203], v[218:219], 0, s[6:7]
	s_addc_u32 s23, s27, 0
	s_add_i32 s26, s60, s39
	global_load_lds_dwordx4 v[202:203], off
	v_lshl_add_u64 v[202:203], s[22:23], 0, v[130:131]
	s_mov_b32 m0, s26
	s_nop 0
	global_load_lds_dwordx4 v[202:203], off
	v_lshl_add_u64 v[202:203], s[22:23], 0, v[134:135]
	s_add_i32 m0, s26, 0x2000
	s_nop 0
	global_load_lds_dwordx4 v[202:203], off
	v_lshl_add_u64 v[202:203], v[220:221], 0, s[6:7]
	s_mov_b32 m0, s47
	s_nop 0
	global_load_lds_dwordx4 v[202:203], off
	v_lshl_add_u64 v[202:203], v[222:223], 0, s[6:7]
	s_mov_b32 m0, s48
	s_nop 0
	global_load_lds_dwordx4 v[202:203], off
	s_waitcnt vmcnt(8)
	s_waitcnt lgkmcnt(0)
	s_barrier
	v_mfma_f32_16x16x32_bf16 v[60:63], v[144:147], v[182:185], v[60:63]
	v_mfma_f32_16x16x32_bf16 v[56:59], v[158:161], v[182:185], v[56:59]
	v_mfma_f32_16x16x32_bf16 v[52:55], v[144:147], v[190:193], v[52:55]
	v_mfma_f32_16x16x32_bf16 v[48:51], v[158:161], v[190:193], v[48:51]
	v_mfma_f32_16x16x32_bf16 v[28:31], v[144:147], v[198:201], v[28:31]
	v_mfma_f32_16x16x32_bf16 v[24:27], v[158:161], v[198:201], v[24:27]
	v_mfma_f32_16x16x32_bf16 v[20:23], v[144:147], v[210:213], v[20:23]
	v_mfma_f32_16x16x32_bf16 v[16:19], v[158:161], v[210:213], v[16:19]
	v_mfma_f32_16x16x32_bf16 v[60:63], v[148:151], v[186:189], v[60:63]
	v_mfma_f32_16x16x32_bf16 v[56:59], v[162:165], v[186:189], v[56:59]
	v_mfma_f32_16x16x32_bf16 v[52:55], v[148:151], v[194:197], v[52:55]
	v_mfma_f32_16x16x32_bf16 v[48:51], v[162:165], v[194:197], v[48:51]
	v_mfma_f32_16x16x32_bf16 v[28:31], v[148:151], v[206:209], v[28:31]
	v_mfma_f32_16x16x32_bf16 v[24:27], v[162:165], v[206:209], v[24:27]
	v_mfma_f32_16x16x32_bf16 v[20:23], v[148:151], v[214:217], v[20:23]
	v_mfma_f32_16x16x32_bf16 v[16:19], v[162:165], v[214:217], v[16:19]
	v_mfma_f32_16x16x32_bf16 v[44:47], v[166:169], v[182:185], v[44:47]
	v_mfma_f32_16x16x32_bf16 v[40:43], v[174:177], v[182:185], v[40:43]
	v_mfma_f32_16x16x32_bf16 v[36:39], v[166:169], v[190:193], v[36:39]
	v_mfma_f32_16x16x32_bf16 v[32:35], v[174:177], v[190:193], v[32:35]
	v_mfma_f32_16x16x32_bf16 v[12:15], v[166:169], v[198:201], v[12:15]
	v_mfma_f32_16x16x32_bf16 v[8:11], v[174:177], v[198:201], v[8:11]
	v_mfma_f32_16x16x32_bf16 v[4:7], v[166:169], v[210:213], v[4:7]
	v_mfma_f32_16x16x32_bf16 v[0:3], v[174:177], v[210:213], v[0:3]
	v_mfma_f32_16x16x32_bf16 v[44:47], v[170:173], v[186:189], v[44:47]
	v_mfma_f32_16x16x32_bf16 v[40:43], v[178:181], v[186:189], v[40:43]
	v_mfma_f32_16x16x32_bf16 v[36:39], v[170:173], v[194:197], v[36:39]
	v_mfma_f32_16x16x32_bf16 v[32:35], v[178:181], v[194:197], v[32:35]
	v_mfma_f32_16x16x32_bf16 v[12:15], v[170:173], v[206:209], v[12:15]
	v_mfma_f32_16x16x32_bf16 v[8:11], v[178:181], v[206:209], v[8:11]
	v_mfma_f32_16x16x32_bf16 v[4:7], v[170:173], v[214:217], v[4:7]
	v_mfma_f32_16x16x32_bf16 v[0:3], v[178:181], v[214:217], v[0:3]
	s_barrier
	s_add_i32 s58, s58, 2
	s_add_u32 s56, s56, 0x100
	s_addc_u32 s57, s57, 0
	s_cmpk_gt_u32 s58, 0x55
	s_mov_b64 s[22:23], s[24:25]
	s_cbranch_scc0 .LBB0_867
	s_and_b64 vcc, exec, s[8:9]
	s_cbranch_vccz .LBB0_870
	s_barrier

; #define PG8_STAGE(bufoff, gbase, voff) do { _Pragma("unroll") for (int _i = 0; _i < 2; ++_i) \
;         __builtin_amdgcn_global_load_lds((const unsigned*)((const char*)(gbase) + (voff)[_i]), (PG8_LAS unsigned*)(lds + (bufoff) + ldsw + _i * 8192), 16, 0, 0); } while (0)
; #define PG8_LDA(dst, b, h) do { _Pragma("unroll") for (int m = 0; m < 4; ++m) _Pragma("unroll") for (int k = 0; k < 2; ++k) dst[m][k] = *(const PG8_LAS bf16x8*)(lds + PG8_SA(b, h) + aoff + m * 2048 + k * 1024); } while (0)
; #define PG8_LDB(dst, b, h) do { _Pragma("unroll") for (int n = 0; n < 2; ++n) _Pragma("unroll") for (int k = 0; k < 2; ++k) dst[n][k] = *(const PG8_LAS bf16x8*)(lds + PG8_SB(b, h) + boff + n * 2048 + k * 1024); } while (0)
; #define PG8_MMA(ai, bj, At, Bt) do { __builtin_amdgcn_s_setprio(1); _Pragma("unroll") for (int m = 0; m < 4; ++m) _Pragma("unroll") for (int n = 0; n < 2; ++n) _Pragma("unroll") for (int k = 0; k < 2; ++k) \
;         acc[ai][bj][m][n] = __builtin_amdgcn_mfma_f32_16x16x32_bf16(Bt[n][k], At[m][k], acc[ai][bj][m][n], 0, 0, 0); __builtin_amdgcn_s_setprio(0); } while (0)
; #define PG8_WAIT_V(n) asm volatile("s_waitcnt vmcnt(" #n ")" ::: "memory")
; #define PG8_WAIT_L(n) asm volatile("s_waitcnt lgkmcnt(" #n ")" ::: "memory")
; template <class Epi, class Sched, bool ALIGN_EPI = false, bool SP2 = false>
; __device__ __forceinline__ void gemm_phase(PG8_LAS unsigned char* lds, const Gemm g, const Sched& S, const Epi& E, const int wv0) {
;     ...
;         for (int t = 0; t < nt; t += 2) {
;             const bool last = (t == nt - 2);
;             const char* a1 = cA + (size_t)(t + 1) * kstep;
;             const char* a2 = last ? nA : cA + (size_t)(t + 2) * kstep; const char* b2 = last ? nB : cB + (size_t)(t + 2) * kstep;
;             const char* a3 = a2 + kstep; const char* b3 = b2 + kstep;
;             if constexpr (SP2) {
;             PG8_LDB(B0, 0, 0); PG8_LDB(B1, 0, 1); PG8_SCHED; PG8_LDA(At, 0, 0); PG8_STAGE(PG8_SA(1, 1), a1 + hstepA, voffA);
;             PG8_WAIT_V(8); PG8_WAIT_L(0); PG8_BAR; PG8_MMA(0, 0, At, B0); PG8_MMA(0, 1, At, B1); PG8_BAR; PG8_SCHED;
;             PG8_LDA(At, 0, 1); PG8_STAGE(PG8_SB(0, 0), b2, voffB); PG8_STAGE(PG8_SB(0, 1), b2 + hstepB, voffB); PG8_STAGE(PG8_SA(0, 0), a2, voffA);
;             PG8_WAIT_V(8); PG8_WAIT_L(0); PG8_BAR; PG8_MMA(1, 0, At, B0); PG8_MMA(1, 1, At, B1); PG8_BAR; PG8_SCHED;
.LBB0_1608:
	ds_read_b128 v[144:147], v155
	ds_read_b128 v[148:151], v155 offset:1024
	ds_read_b128 v[158:161], v155 offset:2048
	ds_read_b128 v[162:165], v155 offset:3072
	ds_read_b128 v[166:169], v156
	ds_read_b128 v[170:173], v156 offset:1024
	ds_read_b128 v[174:177], v156 offset:2048
	ds_read_b128 v[178:181], v156 offset:3072
	ds_read_b128 v[182:185], v157
	ds_read_b128 v[186:189], v157 offset:1024
	ds_read_b128 v[190:193], v157 offset:2048
	ds_read_b128 v[194:197], v157 offset:3072
	ds_read_b128 v[198:201], v157 offset:4096
	ds_read_b128 v[206:209], v157 offset:5120
	ds_read_b128 v[210:213], v157 offset:6144
	ds_read_b128 v[214:217], v157 offset:7168
	s_add_u32 s30, s28, 0xfff80080
	s_addc_u32 s31, s29, -1
	s_cmp_eq_u32 s56, 28
	s_cselect_b32 s35, s23, s31
	s_cselect_b32 s34, s22, s30
	s_cselect_b32 s31, s25, s21
	s_cselect_b32 s30, s24, s19
	s_add_i32 m0, s27, 0xc000
	v_lshl_add_u64 v[202:203], s[28:29], 0, v[138:139]
	global_load_lds_dwordx4 v[202:203], off
	v_lshl_add_u64 v[202:203], s[28:29], 0, v[136:137]
	s_add_i32 m0, s27, 0xe000
	s_nop 0
	global_load_lds_dwordx4 v[202:203], off
	s_waitcnt vmcnt(8)
	s_waitcnt lgkmcnt(0)
	s_barrier
	v_mfma_f32_16x16x32_bf16 v[124:127], v[144:147], v[182:185], v[124:127]
	v_mfma_f32_16x16x32_bf16 v[120:123], v[158:161], v[182:185], v[120:123]
	v_mfma_f32_16x16x32_bf16 v[116:119], v[144:147], v[190:193], v[116:119]
	v_mfma_f32_16x16x32_bf16 v[112:115], v[158:161], v[190:193], v[112:115]
	v_mfma_f32_16x16x32_bf16 v[92:95], v[144:147], v[198:201], v[92:95]
	v_mfma_f32_16x16x32_bf16 v[88:91], v[158:161], v[198:201], v[88:91]
	v_mfma_f32_16x16x32_bf16 v[84:87], v[144:147], v[210:213], v[84:87]
	v_mfma_f32_16x16x32_bf16 v[80:83], v[158:161], v[210:213], v[80:83]
	v_mfma_f32_16x16x32_bf16 v[124:127], v[148:151], v[186:189], v[124:127]
	v_mfma_f32_16x16x32_bf16 v[120:123], v[162:165], v[186:189], v[120:123]
	v_mfma_f32_16x16x32_bf16 v[116:119], v[148:151], v[194:197], v[116:119]
	v_mfma_f32_16x16x32_bf16 v[112:115], v[162:165], v[194:197], v[112:115]
	v_mfma_f32_16x16x32_bf16 v[92:95], v[148:151], v[206:209], v[92:95]
	v_mfma_f32_16x16x32_bf16 v[88:91], v[162:165], v[206:209], v[88:91]
	v_mfma_f32_16x16x32_bf16 v[84:87], v[148:151], v[214:217], v[84:87]
	v_mfma_f32_16x16x32_bf16 v[80:83], v[162:165], v[214:217], v[80:83]
	v_mfma_f32_16x16x32_bf16 v[108:111], v[166:169], v[182:185], v[108:111]
	v_mfma_f32_16x16x32_bf16 v[104:107], v[174:177], v[182:185], v[104:107]
	v_mfma_f32_16x16x32_bf16 v[100:103], v[166:169], v[190:193], v[100:103]
	v_mfma_f32_16x16x32_bf16 v[96:99], v[174:177], v[190:193], v[96:99]
	v_mfma_f32_16x16x32_bf16 v[76:79], v[166:169], v[198:201], v[76:79]
	v_mfma_f32_16x16x32_bf16 v[72:75], v[174:177], v[198:201], v[72:75]
	v_mfma_f32_16x16x32_bf16 v[68:71], v[166:169], v[210:213], v[68:71]
	v_mfma_f32_16x16x32_bf16 v[64:67], v[174:177], v[210:213], v[64:67]
	v_mfma_f32_16x16x32_bf16 v[108:111], v[170:173], v[186:189], v[108:111]
	v_mfma_f32_16x16x32_bf16 v[104:107], v[178:181], v[186:189], v[104:107]
	v_mfma_f32_16x16x32_bf16 v[100:103], v[170:173], v[194:197], v[100:103]
	v_mfma_f32_16x16x32_bf16 v[96:99], v[178:181], v[194:197], v[96:99]
	v_mfma_f32_16x16x32_bf16 v[76:79], v[170:173], v[206:209], v[76:79]
	v_mfma_f32_16x16x32_bf16 v[72:75], v[178:181], v[206:209], v[72:75]
	v_mfma_f32_16x16x32_bf16 v[68:71], v[170:173], v[214:217], v[68:71]
	v_mfma_f32_16x16x32_bf16 v[64:67], v[178:181], v[214:217], v[64:67]
	s_barrier
	ds_read_b128 v[182:185], v157 offset:16384
	ds_read_b128 v[186:189], v157 offset:17408
	ds_read_b128 v[190:193], v157 offset:18432
	ds_read_b128 v[194:197], v157 offset:19456
	ds_read_b128 v[198:201], v157 offset:20480
	ds_read_b128 v[206:209], v157 offset:21504
	ds_read_b128 v[210:213], v157 offset:22528
	ds_read_b128 v[214:217], v157 offset:23552
	s_add_i32 s57, s53, s45
	s_mov_b32 m0, s57
	v_lshl_add_u64 v[202:203], s[30:31], 0, v[130:131]
	global_load_lds_dwordx4 v[202:203], off
	s_add_i32 m0, s57, 0x2000
	s_add_u32 s58, s30, 0x80000
	v_lshl_add_u64 v[218:219], s[30:31], 0, v[134:135]
	s_addc_u32 s59, s31, 0
	s_add_i32 s57, s54, s45
	global_load_lds_dwordx4 v[218:219], off
	v_lshl_add_u64 v[220:221], s[58:59], 0, v[130:131]
	s_mov_b32 m0, s57
	v_lshl_add_u64 v[222:223], s[34:35], 0, v[132:133]
	global_load_lds_dwordx4 v[220:221], off
	v_lshl_add_u64 v[220:221], s[58:59], 0, v[134:135]
	s_add_i32 m0, s57, 0x2000
	s_nop 0
	global_load_lds_dwordx4 v[220:221], off
	v_lshl_add_u64 v[220:221], s[34:35], 0, v[128:129]
	s_mov_b32 m0, s27
	s_nop 0
	global_load_lds_dwordx4 v[220:221], off
	s_mov_b32 m0, s46
	s_nop 0
	global_load_lds_dwordx4 v[222:223], off
	s_waitcnt vmcnt(8)
	s_waitcnt lgkmcnt(0)
	s_barrier
; #define PG8_STAGE(bufoff, gbase, voff) do { _Pragma("unroll") for (int _i = 0; _i < 2; ++_i) \
;         __builtin_amdgcn_global_load_lds((const unsigned*)((const char*)(gbase) + (voff)[_i]), (PG8_LAS unsigned*)(lds + (bufoff) + ldsw + _i * 8192), 16, 0, 0); } while (0)
; #define PG8_LDA(dst, b, h) do { _Pragma("unroll") for (int m = 0; m < 4; ++m) _Pragma("unroll") for (int k = 0; k < 2; ++k) dst[m][k] = *(const PG8_LAS bf16x8*)(lds + PG8_SA(b, h) + aoff + m * 2048 + k * 1024); } while (0)
; #define PG8_LDB(dst, b, h) do { _Pragma("unroll") for (int n = 0; n < 2; ++n) _Pragma("unroll") for (int k = 0; k < 2; ++k) dst[n][k] = *(const PG8_LAS bf16x8*)(lds + PG8_SB(b, h) + boff + n * 2048 + k * 1024); } while (0)
; #define PG8_MMA(ai, bj, At, Bt) do { __builtin_amdgcn_s_setprio(1); _Pragma("unroll") for (int m = 0; m < 4; ++m) _Pragma("unroll") for (int n = 0; n < 2; ++n) _Pragma("unroll") for (int k = 0; k < 2; ++k) \
;         acc[ai][bj][m][n] = __builtin_amdgcn_mfma_f32_16x16x32_bf16(Bt[n][k], At[m][k], acc[ai][bj][m][n], 0, 0, 0); __builtin_amdgcn_s_setprio(0); } while (0)
; #define PG8_WAIT_V(n) asm volatile("s_waitcnt vmcnt(" #n ")" ::: "memory")
; #define PG8_WAIT_L(n) asm volatile("s_waitcnt lgkmcnt(" #n ")" ::: "memory")
; #define PG8_BAR __builtin_amdgcn_s_barrier()
; #define PG8_SCHED __builtin_amdgcn_sched_barrier(0)
; template <class Epi, class Sched, bool ALIGN_EPI = false, bool SP2 = false>
; __device__ __forceinline__ void gemm_phase(PG8_LAS unsigned char* lds, const Gemm g, const Sched& S, const Epi& E, const int wv0) {
;     ...
;             PG8_WAIT_V(8); PG8_WAIT_L(0); PG8_BAR; PG8_MMA(1, 0, At, B0); PG8_MMA(1, 1, At, B1); PG8_BAR; PG8_SCHED;
;             PG8_LDB(B0, 1, 0); PG8_LDB(B1, 1, 1); PG8_SCHED; PG8_LDA(At, 1, 0); PG8_STAGE(PG8_SA(0, 1), a2 + hstepA, voffA);
;             PG8_WAIT_V(8); PG8_WAIT_L(0); PG8_BAR; PG8_MMA(0, 0, At, B0); PG8_MMA(0, 1, At, B1); PG8_BAR; PG8_SCHED;
	v_mfma_f32_16x16x32_bf16 v[60:63], v[144:147], v[182:185], v[60:63]
	v_mfma_f32_16x16x32_bf16 v[56:59], v[158:161], v[182:185], v[56:59]
	v_mfma_f32_16x16x32_bf16 v[52:55], v[144:147], v[190:193], v[52:55]
	v_mfma_f32_16x16x32_bf16 v[48:51], v[158:161], v[190:193], v[48:51]
	v_mfma_f32_16x16x32_bf16 v[28:31], v[144:147], v[198:201], v[28:31]
	v_mfma_f32_16x16x32_bf16 v[24:27], v[158:161], v[198:201], v[24:27]
	v_mfma_f32_16x16x32_bf16 v[20:23], v[144:147], v[210:213], v[20:23]
	v_mfma_f32_16x16x32_bf16 v[16:19], v[158:161], v[210:213], v[16:19]
	v_mfma_f32_16x16x32_bf16 v[60:63], v[148:151], v[186:189], v[60:63]
	v_mfma_f32_16x16x32_bf16 v[56:59], v[162:165], v[186:189], v[56:59]
	v_mfma_f32_16x16x32_bf16 v[52:55], v[148:151], v[194:197], v[52:55]
	v_mfma_f32_16x16x32_bf16 v[48:51], v[162:165], v[194:197], v[48:51]
	v_mfma_f32_16x16x32_bf16 v[28:31], v[148:151], v[206:209], v[28:31]
	v_mfma_f32_16x16x32_bf16 v[24:27], v[162:165], v[206:209], v[24:27]
	v_mfma_f32_16x16x32_bf16 v[20:23], v[148:151], v[214:217], v[20:23]
	v_mfma_f32_16x16x32_bf16 v[16:19], v[162:165], v[214:217], v[16:19]
	v_mfma_f32_16x16x32_bf16 v[44:47], v[166:169], v[182:185], v[44:47]
	v_mfma_f32_16x16x32_bf16 v[40:43], v[174:177], v[182:185], v[40:43]
	v_mfma_f32_16x16x32_bf16 v[36:39], v[166:169], v[190:193], v[36:39]
	v_mfma_f32_16x16x32_bf16 v[32:35], v[174:177], v[190:193], v[32:35]
	v_mfma_f32_16x16x32_bf16 v[12:15], v[166:169], v[198:201], v[12:15]
	v_mfma_f32_16x16x32_bf16 v[8:11], v[174:177], v[198:201], v[8:11]
	v_mfma_f32_16x16x32_bf16 v[4:7], v[166:169], v[210:213], v[4:7]
	v_mfma_f32_16x16x32_bf16 v[0:3], v[174:177], v[210:213], v[0:3]
	v_mfma_f32_16x16x32_bf16 v[44:47], v[170:173], v[186:189], v[44:47]
	v_mfma_f32_16x16x32_bf16 v[40:43], v[178:181], v[186:189], v[40:43]
	v_mfma_f32_16x16x32_bf16 v[36:39], v[170:173], v[194:197], v[36:39]
	v_mfma_f32_16x16x32_bf16 v[32:35], v[178:181], v[194:197], v[32:35]
	v_mfma_f32_16x16x32_bf16 v[12:15], v[170:173], v[206:209], v[12:15]
	v_mfma_f32_16x16x32_bf16 v[8:11], v[178:181], v[206:209], v[8:11]
	v_mfma_f32_16x16x32_bf16 v[4:7], v[170:173], v[214:217], v[4:7]
	v_mfma_f32_16x16x32_bf16 v[0:3], v[178:181], v[214:217], v[0:3]
	s_barrier
	s_add_i32 s57, 0, 0x18000
	s_add_i32 s58, 0, 0x1c000
	v_add_u32_e32 v162, s57, v153
	v_add_u32_e32 v178, s58, v153
	ds_read_b128 v[144:147], v162
	ds_read_b128 v[148:151], v162 offset:1024
	ds_read_b128 v[158:161], v162 offset:2048
	ds_read_b128 v[162:165], v162 offset:3072
	ds_read_b128 v[166:169], v178
	ds_read_b128 v[170:173], v178 offset:1024
	ds_read_b128 v[174:177], v178 offset:2048
	ds_read_b128 v[178:181], v178 offset:3072
	s_add_u32 s34, s34, 0x80000
	s_addc_u32 s35, s35, 0
	s_mov_b32 m0, s47
	v_lshl_add_u64 v[224:225], s[34:35], 0, v[128:129]
	ds_read_b128 v[182:185], v157 offset:32768
	ds_read_b128 v[186:189], v157 offset:33792
	ds_read_b128 v[190:193], v157 offset:34816
	ds_read_b128 v[194:197], v157 offset:35840
	ds_read_b128 v[198:201], v157 offset:36864
	ds_read_b128 v[206:209], v157 offset:37888
	ds_read_b128 v[210:213], v157 offset:38912
	ds_read_b128 v[214:217], v157 offset:39936
	global_load_lds_dwordx4 v[224:225], off
	v_lshl_add_u64 v[224:225], s[34:35], 0, v[132:133]
	s_mov_b32 m0, s48
	s_nop 0
	global_load_lds_dwordx4 v[224:225], off
	s_waitcnt vmcnt(8)
	s_waitcnt lgkmcnt(0)
	s_barrier
	v_mfma_f32_16x16x32_bf16 v[124:127], v[144:147], v[182:185], v[124:127]
	v_mfma_f32_16x16x32_bf16 v[120:123], v[158:161], v[182:185], v[120:123]
	v_mfma_f32_16x16x32_bf16 v[116:119], v[144:147], v[190:193], v[116:119]
	v_mfma_f32_16x16x32_bf16 v[112:115], v[158:161], v[190:193], v[112:115]
	v_mfma_f32_16x16x32_bf16 v[92:95], v[144:147], v[198:201], v[92:95]
	v_mfma_f32_16x16x32_bf16 v[88:91], v[158:161], v[198:201], v[88:91]
	v_mfma_f32_16x16x32_bf16 v[84:87], v[144:147], v[210:213], v[84:87]
	v_mfma_f32_16x16x32_bf16 v[80:83], v[158:161], v[210:213], v[80:83]
	v_mfma_f32_16x16x32_bf16 v[124:127], v[148:151], v[186:189], v[124:127]
	v_mfma_f32_16x16x32_bf16 v[120:123], v[162:165], v[186:189], v[120:123]
	v_mfma_f32_16x16x32_bf16 v[116:119], v[148:151], v[194:197], v[116:119]
	v_mfma_f32_16x16x32_bf16 v[112:115], v[162:165], v[194:197], v[112:115]
	v_mfma_f32_16x16x32_bf16 v[92:95], v[148:151], v[206:209], v[92:95]
	v_mfma_f32_16x16x32_bf16 v[88:91], v[162:165], v[206:209], v[88:91]
	v_mfma_f32_16x16x32_bf16 v[84:87], v[148:151], v[214:217], v[84:87]
	v_mfma_f32_16x16x32_bf16 v[80:83], v[162:165], v[214:217], v[80:83]
	v_mfma_f32_16x16x32_bf16 v[108:111], v[166:169], v[182:185], v[108:111]
	v_mfma_f32_16x16x32_bf16 v[104:107], v[174:177], v[182:185], v[104:107]
	v_mfma_f32_16x16x32_bf16 v[100:103], v[166:169], v[190:193], v[100:103]
	v_mfma_f32_16x16x32_bf16 v[96:99], v[174:177], v[190:193], v[96:99]
	v_mfma_f32_16x16x32_bf16 v[76:79], v[166:169], v[198:201], v[76:79]
	v_mfma_f32_16x16x32_bf16 v[72:75], v[174:177], v[198:201], v[72:75]
	v_mfma_f32_16x16x32_bf16 v[68:71], v[166:169], v[210:213], v[68:71]
	v_mfma_f32_16x16x32_bf16 v[64:67], v[174:177], v[210:213], v[64:67]
	v_mfma_f32_16x16x32_bf16 v[108:111], v[170:173], v[186:189], v[108:111]
	v_mfma_f32_16x16x32_bf16 v[104:107], v[178:181], v[186:189], v[104:107]
	v_mfma_f32_16x16x32_bf16 v[100:103], v[170:173], v[194:197], v[100:103]
	v_mfma_f32_16x16x32_bf16 v[96:99], v[178:181], v[194:197], v[96:99]
	v_mfma_f32_16x16x32_bf16 v[76:79], v[170:173], v[206:209], v[76:79]
	v_mfma_f32_16x16x32_bf16 v[72:75], v[178:181], v[206:209], v[72:75]
	v_mfma_f32_16x16x32_bf16 v[68:71], v[170:173], v[214:217], v[68:71]
	v_mfma_f32_16x16x32_bf16 v[64:67], v[178:181], v[214:217], v[64:67]
	s_barrier
; #define PG8_STAGE(bufoff, gbase, voff) do { _Pragma("unroll") for (int _i = 0; _i < 2; ++_i) \
;         __builtin_amdgcn_global_load_lds((const unsigned*)((const char*)(gbase) + (voff)[_i]), (PG8_LAS unsigned*)(lds + (bufoff) + ldsw + _i * 8192), 16, 0, 0); } while (0)
; #define PG8_LDA(dst, b, h) do { _Pragma("unroll") for (int m = 0; m < 4; ++m) _Pragma("unroll") for (int k = 0; k < 2; ++k) dst[m][k] = *(const PG8_LAS bf16x8*)(lds + PG8_SA(b, h) + aoff + m * 2048 + k * 1024); } while (0)
; #define PG8_MMA(ai, bj, At, Bt) do { __builtin_amdgcn_s_setprio(1); _Pragma("unroll") for (int m = 0; m < 4; ++m) _Pragma("unroll") for (int n = 0; n < 2; ++n) _Pragma("unroll") for (int k = 0; k < 2; ++k) \
;         acc[ai][bj][m][n] = __builtin_amdgcn_mfma_f32_16x16x32_bf16(Bt[n][k], At[m][k], acc[ai][bj][m][n], 0, 0, 0); __builtin_amdgcn_s_setprio(0); } while (0)
; #define PG8_WAIT_V(n) asm volatile("s_waitcnt vmcnt(" #n ")" ::: "memory")
; #define PG8_WAIT_L(n) asm volatile("s_waitcnt lgkmcnt(" #n ")" ::: "memory")
; #define PG8_BAR __builtin_amdgcn_s_barrier()
; #define PG8_SCHED __builtin_amdgcn_sched_barrier(0)
; template <class Epi, class Sched, bool ALIGN_EPI = false, bool SP2 = false>
; __device__ __forceinline__ void gemm_phase(PG8_LAS unsigned char* lds, const Gemm g, const Sched& S, const Epi& E, const int wv0) {
;     ...
;             PG8_LDA(At, 1, 1); PG8_STAGE(PG8_SB(1, 0), b3, voffB); PG8_STAGE(PG8_SB(1, 1), b3 + hstepB, voffB); PG8_STAGE(PG8_SA(1, 0), a3, voffA);
;             PG8_WAIT_V(8); PG8_WAIT_L(0); PG8_BAR; PG8_MMA(1, 0, At, B0); PG8_MMA(1, 1, At, B1); PG8_BAR; PG8_SCHED;
;     ...
;         if constexpr (ALIGN_EPI) { if (wr == 0) PG8_BAR; }
	s_add_i32 s34, s57, s45
	v_lshl_add_u64 v[202:203], v[202:203], 0, s[8:9]
	s_mov_b32 m0, s34
	ds_read_b128 v[182:185], v157 offset:49152
	ds_read_b128 v[186:189], v157 offset:50176
	ds_read_b128 v[190:193], v157 offset:51200
	ds_read_b128 v[194:197], v157 offset:52224
	ds_read_b128 v[198:201], v157 offset:53248
	ds_read_b128 v[206:209], v157 offset:54272
	ds_read_b128 v[210:213], v157 offset:55296
	ds_read_b128 v[214:217], v157 offset:56320
	global_load_lds_dwordx4 v[202:203], off
	s_add_i32 m0, s34, 0x2000
	s_add_u32 s30, s30, 0x80080
	v_lshl_add_u64 v[202:203], v[218:219], 0, s[8:9]
	s_addc_u32 s31, s31, 0
	s_add_i32 s34, s58, s45
	global_load_lds_dwordx4 v[202:203], off
	v_lshl_add_u64 v[202:203], s[30:31], 0, v[130:131]
	s_mov_b32 m0, s34
	s_nop 0
	global_load_lds_dwordx4 v[202:203], off
	v_lshl_add_u64 v[202:203], s[30:31], 0, v[134:135]
	s_add_i32 m0, s34, 0x2000
	s_nop 0
	global_load_lds_dwordx4 v[202:203], off
	v_lshl_add_u64 v[202:203], v[220:221], 0, s[8:9]
	s_mov_b32 m0, s50
	s_nop 0
	global_load_lds_dwordx4 v[202:203], off
	v_lshl_add_u64 v[202:203], v[222:223], 0, s[8:9]
	s_mov_b32 m0, s51
	s_nop 0
	global_load_lds_dwordx4 v[202:203], off
	s_waitcnt vmcnt(8)
	s_waitcnt lgkmcnt(0)
	s_barrier
	v_mfma_f32_16x16x32_bf16 v[60:63], v[144:147], v[182:185], v[60:63]
	v_mfma_f32_16x16x32_bf16 v[56:59], v[158:161], v[182:185], v[56:59]
	v_mfma_f32_16x16x32_bf16 v[52:55], v[144:147], v[190:193], v[52:55]
	v_mfma_f32_16x16x32_bf16 v[48:51], v[158:161], v[190:193], v[48:51]
	v_mfma_f32_16x16x32_bf16 v[28:31], v[144:147], v[198:201], v[28:31]
	v_mfma_f32_16x16x32_bf16 v[24:27], v[158:161], v[198:201], v[24:27]
	v_mfma_f32_16x16x32_bf16 v[20:23], v[144:147], v[210:213], v[20:23]
	v_mfma_f32_16x16x32_bf16 v[16:19], v[158:161], v[210:213], v[16:19]
	v_mfma_f32_16x16x32_bf16 v[60:63], v[148:151], v[186:189], v[60:63]
	v_mfma_f32_16x16x32_bf16 v[56:59], v[162:165], v[186:189], v[56:59]
	v_mfma_f32_16x16x32_bf16 v[52:55], v[148:151], v[194:197], v[52:55]
	v_mfma_f32_16x16x32_bf16 v[48:51], v[162:165], v[194:197], v[48:51]
	v_mfma_f32_16x16x32_bf16 v[28:31], v[148:151], v[206:209], v[28:31]
	v_mfma_f32_16x16x32_bf16 v[24:27], v[162:165], v[206:209], v[24:27]
	v_mfma_f32_16x16x32_bf16 v[20:23], v[148:151], v[214:217], v[20:23]
	v_mfma_f32_16x16x32_bf16 v[16:19], v[162:165], v[214:217], v[16:19]
	v_mfma_f32_16x16x32_bf16 v[44:47], v[166:169], v[182:185], v[44:47]
	v_mfma_f32_16x16x32_bf16 v[40:43], v[174:177], v[182:185], v[40:43]
	v_mfma_f32_16x16x32_bf16 v[36:39], v[166:169], v[190:193], v[36:39]
	v_mfma_f32_16x16x32_bf16 v[32:35], v[174:177], v[190:193], v[32:35]
	v_mfma_f32_16x16x32_bf16 v[12:15], v[166:169], v[198:201], v[12:15]
	v_mfma_f32_16x16x32_bf16 v[8:11], v[174:177], v[198:201], v[8:11]
	v_mfma_f32_16x16x32_bf16 v[4:7], v[166:169], v[210:213], v[4:7]
	v_mfma_f32_16x16x32_bf16 v[0:3], v[174:177], v[210:213], v[0:3]
	v_mfma_f32_16x16x32_bf16 v[44:47], v[170:173], v[186:189], v[44:47]
	v_mfma_f32_16x16x32_bf16 v[40:43], v[178:181], v[186:189], v[40:43]
	v_mfma_f32_16x16x32_bf16 v[36:39], v[170:173], v[194:197], v[36:39]
	v_mfma_f32_16x16x32_bf16 v[32:35], v[178:181], v[194:197], v[32:35]
	v_mfma_f32_16x16x32_bf16 v[12:15], v[170:173], v[206:209], v[12:15]
	v_mfma_f32_16x16x32_bf16 v[8:11], v[178:181], v[206:209], v[8:11]
	v_mfma_f32_16x16x32_bf16 v[4:7], v[170:173], v[214:217], v[4:7]
	v_mfma_f32_16x16x32_bf16 v[0:3], v[178:181], v[214:217], v[0:3]
	s_barrier
	s_add_i32 s56, s56, 2
	s_add_u32 s19, s19, 0x100
	s_addc_u32 s21, s21, 0
	s_add_u32 s28, s28, 0x100
	s_addc_u32 s29, s29, 0
	s_cmp_gt_u32 s56, 29
	s_cbranch_scc0 .LBB0_1608
	s_and_b64 vcc, exec, s[10:11]
	s_cbranch_vccz .LBB0_1611
	s_barrier

; #define PG8_STAGE(bufoff, gbase, voff) do { _Pragma("unroll") for (int _i = 0; _i < 2; ++_i) \
;         __builtin_amdgcn_global_load_lds((const unsigned*)((const char*)(gbase) + (voff)[_i]), (PG8_LAS unsigned*)(lds + (bufoff) + ldsw + _i * 8192), 16, 0, 0); } while (0)
; #define PG8_LDA(dst, b, h) do { _Pragma("unroll") for (int m = 0; m < 4; ++m) _Pragma("unroll") for (int k = 0; k < 2; ++k) dst[m][k] = *(const PG8_LAS bf16x8*)(lds + PG8_SA(b, h) + aoff + m * 2048 + k * 1024); } while (0)
; #define PG8_LDB(dst, b, h) do { _Pragma("unroll") for (int n = 0; n < 2; ++n) _Pragma("unroll") for (int k = 0; k < 2; ++k) dst[n][k] = *(const PG8_LAS bf16x8*)(lds + PG8_SB(b, h) + boff + n * 2048 + k * 1024); } while (0)
; #define PG8_MMA(ai, bj, At, Bt) do { __builtin_amdgcn_s_setprio(1); _Pragma("unroll") for (int m = 0; m < 4; ++m) _Pragma("unroll") for (int n = 0; n < 2; ++n) _Pragma("unroll") for (int k = 0; k < 2; ++k) \
;         acc[ai][bj][m][n] = __builtin_amdgcn_mfma_f32_16x16x32_bf16(Bt[n][k], At[m][k], acc[ai][bj][m][n], 0, 0, 0); __builtin_amdgcn_s_setprio(0); } while (0)
; #define PG8_WAIT_V(n) asm volatile("s_waitcnt vmcnt(" #n ")" ::: "memory")
; #define PG8_WAIT_L(n) asm volatile("s_waitcnt lgkmcnt(" #n ")" ::: "memory")
; template <class Epi, class Sched, bool ALIGN_EPI = false, bool SP2 = false>
; __device__ __forceinline__ void gemm_phase(PG8_LAS unsigned char* lds, const Gemm g, const Sched& S, const Epi& E, const int wv0) {
;     ...
;         for (int t = 0; t < nt; t += 2) {
;             const bool last = (t == nt - 2);
;             const char* a1 = cA + (size_t)(t + 1) * kstep;
;             const char* a2 = last ? nA : cA + (size_t)(t + 2) * kstep; const char* b2 = last ? nB : cB + (size_t)(t + 2) * kstep;
;             const char* a3 = a2 + kstep; const char* b3 = b2 + kstep;
;             if constexpr (SP2) {
;             PG8_LDB(B0, 0, 0); PG8_LDB(B1, 0, 1); PG8_SCHED; PG8_LDA(At, 0, 0); PG8_STAGE(PG8_SA(1, 1), a1 + hstepA, voffA);
;             PG8_WAIT_V(8); PG8_WAIT_L(0); PG8_BAR; PG8_MMA(0, 0, At, B0); PG8_MMA(0, 1, At, B1); PG8_BAR; PG8_SCHED;
;             PG8_LDA(At, 0, 1); PG8_STAGE(PG8_SB(0, 0), b2, voffB); PG8_STAGE(PG8_SB(0, 1), b2 + hstepB, voffB); PG8_STAGE(PG8_SA(0, 0), a2, voffA);
;             PG8_WAIT_V(8); PG8_WAIT_L(0); PG8_BAR; PG8_MMA(1, 0, At, B0); PG8_MMA(1, 1, At, B1); PG8_BAR; PG8_SCHED;
.LBB0_1808:
	ds_read_b128 v[144:147], v153
	ds_read_b128 v[156:159], v153 offset:1024
	ds_read_b128 v[160:163], v153 offset:2048
	ds_read_b128 v[164:167], v153 offset:3072
	ds_read_b128 v[168:171], v154
	ds_read_b128 v[172:175], v154 offset:1024
	ds_read_b128 v[176:179], v154 offset:2048
	ds_read_b128 v[180:183], v154 offset:3072
	ds_read_b128 v[184:187], v155
	ds_read_b128 v[188:191], v155 offset:1024
	ds_read_b128 v[192:195], v155 offset:2048
	ds_read_b128 v[196:199], v155 offset:3072
	ds_read_b128 v[200:203], v155 offset:4096
	ds_read_b128 v[204:207], v155 offset:5120
	ds_read_b128 v[208:211], v155 offset:6144
	ds_read_b128 v[212:215], v155 offset:7168
	s_add_u32 s18, s16, 0x100
	s_addc_u32 s19, s17, 0
	s_cmpk_eq_i32 s48, 0x54
	s_cselect_b32 s23, s13, s19
	s_cselect_b32 s22, s12, s18
	s_cselect_b32 s21, s15, s47
	s_cselect_b32 s20, s14, s46
	s_add_i32 m0, s30, 0xc000
	v_lshl_add_u64 v[148:149], s[16:17], 0, v[138:139]
	global_load_lds_dwordx4 v[148:149], off
	v_lshl_add_u64 v[148:149], s[16:17], 0, v[136:137]
	s_add_i32 m0, s30, 0xe000
	s_nop 0
	global_load_lds_dwordx4 v[148:149], off
	s_waitcnt vmcnt(8)
	s_waitcnt lgkmcnt(0)
	s_barrier
	v_mfma_f32_16x16x32_bf16 v[124:127], v[144:147], v[184:187], v[124:127]
	v_mfma_f32_16x16x32_bf16 v[120:123], v[160:163], v[184:187], v[120:123]
	v_mfma_f32_16x16x32_bf16 v[116:119], v[144:147], v[192:195], v[116:119]
	v_mfma_f32_16x16x32_bf16 v[112:115], v[160:163], v[192:195], v[112:115]
	v_mfma_f32_16x16x32_bf16 v[92:95], v[144:147], v[200:203], v[92:95]
	v_mfma_f32_16x16x32_bf16 v[88:91], v[160:163], v[200:203], v[88:91]
	v_mfma_f32_16x16x32_bf16 v[84:87], v[144:147], v[208:211], v[84:87]
	v_mfma_f32_16x16x32_bf16 v[80:83], v[160:163], v[208:211], v[80:83]
	v_mfma_f32_16x16x32_bf16 v[124:127], v[156:159], v[188:191], v[124:127]
	v_mfma_f32_16x16x32_bf16 v[120:123], v[164:167], v[188:191], v[120:123]
	v_mfma_f32_16x16x32_bf16 v[116:119], v[156:159], v[196:199], v[116:119]
	v_mfma_f32_16x16x32_bf16 v[112:115], v[164:167], v[196:199], v[112:115]
	v_mfma_f32_16x16x32_bf16 v[92:95], v[156:159], v[204:207], v[92:95]
	v_mfma_f32_16x16x32_bf16 v[88:91], v[164:167], v[204:207], v[88:91]
	v_mfma_f32_16x16x32_bf16 v[84:87], v[156:159], v[212:215], v[84:87]
	v_mfma_f32_16x16x32_bf16 v[80:83], v[164:167], v[212:215], v[80:83]
	v_mfma_f32_16x16x32_bf16 v[108:111], v[168:171], v[184:187], v[108:111]
	v_mfma_f32_16x16x32_bf16 v[104:107], v[176:179], v[184:187], v[104:107]
	v_mfma_f32_16x16x32_bf16 v[100:103], v[168:171], v[192:195], v[100:103]
	v_mfma_f32_16x16x32_bf16 v[96:99], v[176:179], v[192:195], v[96:99]
	v_mfma_f32_16x16x32_bf16 v[76:79], v[168:171], v[200:203], v[76:79]
	v_mfma_f32_16x16x32_bf16 v[72:75], v[176:179], v[200:203], v[72:75]
	v_mfma_f32_16x16x32_bf16 v[68:71], v[168:171], v[208:211], v[68:71]
	v_mfma_f32_16x16x32_bf16 v[64:67], v[176:179], v[208:211], v[64:67]
	v_mfma_f32_16x16x32_bf16 v[108:111], v[172:175], v[188:191], v[108:111]
	v_mfma_f32_16x16x32_bf16 v[104:107], v[180:183], v[188:191], v[104:107]
	v_mfma_f32_16x16x32_bf16 v[100:103], v[172:175], v[196:199], v[100:103]
	v_mfma_f32_16x16x32_bf16 v[96:99], v[180:183], v[196:199], v[96:99]
	v_mfma_f32_16x16x32_bf16 v[76:79], v[172:175], v[204:207], v[76:79]
	v_mfma_f32_16x16x32_bf16 v[72:75], v[180:183], v[204:207], v[72:75]
	v_mfma_f32_16x16x32_bf16 v[68:71], v[172:175], v[212:215], v[68:71]
	v_mfma_f32_16x16x32_bf16 v[64:67], v[180:183], v[212:215], v[64:67]
	s_barrier
	ds_read_b128 v[184:187], v155 offset:16384
	ds_read_b128 v[188:191], v155 offset:17408
	ds_read_b128 v[192:195], v155 offset:18432
	ds_read_b128 v[196:199], v155 offset:19456
	ds_read_b128 v[200:203], v155 offset:20480
	ds_read_b128 v[204:207], v155 offset:21504
	ds_read_b128 v[208:211], v155 offset:22528
	ds_read_b128 v[212:215], v155 offset:23552
	s_add_i32 s16, s40, s29
	s_mov_b32 m0, s16
	v_lshl_add_u64 v[148:149], s[20:21], 0, v[130:131]
	global_load_lds_dwordx4 v[148:149], off
	s_add_i32 m0, s16, 0x2000
	s_add_u32 s16, s20, 0x160000
	v_lshl_add_u64 v[216:217], s[20:21], 0, v[134:135]
	s_addc_u32 s17, s21, 0
	s_add_i32 s49, s41, s29
	global_load_lds_dwordx4 v[216:217], off
	v_lshl_add_u64 v[218:219], s[16:17], 0, v[130:131]
	s_mov_b32 m0, s49
	v_lshl_add_u64 v[220:221], s[22:23], 0, v[132:133]
	global_load_lds_dwordx4 v[218:219], off
	v_lshl_add_u64 v[218:219], s[16:17], 0, v[134:135]
	s_add_i32 m0, s49, 0x2000
	s_nop 0
	global_load_lds_dwordx4 v[218:219], off
	v_lshl_add_u64 v[218:219], s[22:23], 0, v[128:129]
	s_mov_b32 m0, s30
	s_nop 0
	global_load_lds_dwordx4 v[218:219], off
	s_mov_b32 m0, s31
	s_nop 0
	global_load_lds_dwordx4 v[220:221], off
	s_waitcnt vmcnt(8)
	s_waitcnt lgkmcnt(0)
	s_barrier
; #define PG8_STAGE(bufoff, gbase, voff) do { _Pragma("unroll") for (int _i = 0; _i < 2; ++_i) \
;         __builtin_amdgcn_global_load_lds((const unsigned*)((const char*)(gbase) + (voff)[_i]), (PG8_LAS unsigned*)(lds + (bufoff) + ldsw + _i * 8192), 16, 0, 0); } while (0)
; #define PG8_LDA(dst, b, h) do { _Pragma("unroll") for (int m = 0; m < 4; ++m) _Pragma("unroll") for (int k = 0; k < 2; ++k) dst[m][k] = *(const PG8_LAS bf16x8*)(lds + PG8_SA(b, h) + aoff + m * 2048 + k * 1024); } while (0)
; #define PG8_LDB(dst, b, h) do { _Pragma("unroll") for (int n = 0; n < 2; ++n) _Pragma("unroll") for (int k = 0; k < 2; ++k) dst[n][k] = *(const PG8_LAS bf16x8*)(lds + PG8_SB(b, h) + boff + n * 2048 + k * 1024); } while (0)
; #define PG8_MMA(ai, bj, At, Bt) do { __builtin_amdgcn_s_setprio(1); _Pragma("unroll") for (int m = 0; m < 4; ++m) _Pragma("unroll") for (int n = 0; n < 2; ++n) _Pragma("unroll") for (int k = 0; k < 2; ++k) \
;         acc[ai][bj][m][n] = __builtin_amdgcn_mfma_f32_16x16x32_bf16(Bt[n][k], At[m][k], acc[ai][bj][m][n], 0, 0, 0); __builtin_amdgcn_s_setprio(0); } while (0)
; #define PG8_WAIT_V(n) asm volatile("s_waitcnt vmcnt(" #n ")" ::: "memory")
; #define PG8_WAIT_L(n) asm volatile("s_waitcnt lgkmcnt(" #n ")" ::: "memory")
; #define PG8_BAR __builtin_amdgcn_s_barrier()
; #define PG8_SCHED __builtin_amdgcn_sched_barrier(0)
; template <class Epi, class Sched, bool ALIGN_EPI = false, bool SP2 = false>
; __device__ __forceinline__ void gemm_phase(PG8_LAS unsigned char* lds, const Gemm g, const Sched& S, const Epi& E, const int wv0) {
;     ...
;             PG8_WAIT_V(8); PG8_WAIT_L(0); PG8_BAR; PG8_MMA(1, 0, At, B0); PG8_MMA(1, 1, At, B1); PG8_BAR; PG8_SCHED;
;             PG8_LDB(B0, 1, 0); PG8_LDB(B1, 1, 1); PG8_SCHED; PG8_LDA(At, 1, 0); PG8_STAGE(PG8_SA(0, 1), a2 + hstepA, voffA);
;             PG8_WAIT_V(8); PG8_WAIT_L(0); PG8_BAR; PG8_MMA(0, 0, At, B0); PG8_MMA(0, 1, At, B1); PG8_BAR; PG8_SCHED;
	v_mfma_f32_16x16x32_bf16 v[60:63], v[144:147], v[184:187], v[60:63]
	v_mfma_f32_16x16x32_bf16 v[56:59], v[160:163], v[184:187], v[56:59]
	v_mfma_f32_16x16x32_bf16 v[52:55], v[144:147], v[192:195], v[52:55]
	v_mfma_f32_16x16x32_bf16 v[48:51], v[160:163], v[192:195], v[48:51]
	v_mfma_f32_16x16x32_bf16 v[28:31], v[144:147], v[200:203], v[28:31]
	v_mfma_f32_16x16x32_bf16 v[24:27], v[160:163], v[200:203], v[24:27]
	v_mfma_f32_16x16x32_bf16 v[20:23], v[144:147], v[208:211], v[20:23]
	v_mfma_f32_16x16x32_bf16 v[16:19], v[160:163], v[208:211], v[16:19]
	v_mfma_f32_16x16x32_bf16 v[60:63], v[156:159], v[188:191], v[60:63]
	v_mfma_f32_16x16x32_bf16 v[56:59], v[164:167], v[188:191], v[56:59]
	v_mfma_f32_16x16x32_bf16 v[52:55], v[156:159], v[196:199], v[52:55]
	v_mfma_f32_16x16x32_bf16 v[48:51], v[164:167], v[196:199], v[48:51]
	v_mfma_f32_16x16x32_bf16 v[28:31], v[156:159], v[204:207], v[28:31]
	v_mfma_f32_16x16x32_bf16 v[24:27], v[164:167], v[204:207], v[24:27]
	v_mfma_f32_16x16x32_bf16 v[20:23], v[156:159], v[212:215], v[20:23]
	v_mfma_f32_16x16x32_bf16 v[16:19], v[164:167], v[212:215], v[16:19]
	v_mfma_f32_16x16x32_bf16 v[44:47], v[168:171], v[184:187], v[44:47]
	v_mfma_f32_16x16x32_bf16 v[40:43], v[176:179], v[184:187], v[40:43]
	v_mfma_f32_16x16x32_bf16 v[36:39], v[168:171], v[192:195], v[36:39]
	v_mfma_f32_16x16x32_bf16 v[32:35], v[176:179], v[192:195], v[32:35]
	v_mfma_f32_16x16x32_bf16 v[12:15], v[168:171], v[200:203], v[12:15]
	v_mfma_f32_16x16x32_bf16 v[8:11], v[176:179], v[200:203], v[8:11]
	v_mfma_f32_16x16x32_bf16 v[4:7], v[168:171], v[208:211], v[4:7]
	v_mfma_f32_16x16x32_bf16 v[0:3], v[176:179], v[208:211], v[0:3]
	v_mfma_f32_16x16x32_bf16 v[44:47], v[172:175], v[188:191], v[44:47]
	v_mfma_f32_16x16x32_bf16 v[40:43], v[180:183], v[188:191], v[40:43]
	v_mfma_f32_16x16x32_bf16 v[36:39], v[172:175], v[196:199], v[36:39]
	v_mfma_f32_16x16x32_bf16 v[32:35], v[180:183], v[196:199], v[32:35]
	v_mfma_f32_16x16x32_bf16 v[12:15], v[172:175], v[204:207], v[12:15]
	v_mfma_f32_16x16x32_bf16 v[8:11], v[180:183], v[204:207], v[8:11]
	v_mfma_f32_16x16x32_bf16 v[4:7], v[172:175], v[212:215], v[4:7]
	v_mfma_f32_16x16x32_bf16 v[0:3], v[180:183], v[212:215], v[0:3]
	s_barrier
	s_add_i32 s49, 0, 0x18000
	s_add_i32 s50, 0, 0x1c000
	v_add_u32_e32 v164, s49, v151
	v_add_u32_e32 v180, s50, v151
	ds_read_b128 v[144:147], v164
	ds_read_b128 v[156:159], v164 offset:1024
	ds_read_b128 v[160:163], v164 offset:2048
	ds_read_b128 v[164:167], v164 offset:3072
	ds_read_b128 v[168:171], v180
	ds_read_b128 v[172:175], v180 offset:1024
	ds_read_b128 v[176:179], v180 offset:2048
	ds_read_b128 v[180:183], v180 offset:3072
	s_add_u32 s16, s22, 0x160000
	s_addc_u32 s17, s23, 0
	s_mov_b32 m0, s34
	v_lshl_add_u64 v[222:223], s[16:17], 0, v[128:129]
	ds_read_b128 v[184:187], v155 offset:32768
	ds_read_b128 v[188:191], v155 offset:33792
	ds_read_b128 v[192:195], v155 offset:34816
	ds_read_b128 v[196:199], v155 offset:35840
	ds_read_b128 v[200:203], v155 offset:36864
	ds_read_b128 v[204:207], v155 offset:37888
	ds_read_b128 v[208:211], v155 offset:38912
	ds_read_b128 v[212:215], v155 offset:39936
	global_load_lds_dwordx4 v[222:223], off
	v_lshl_add_u64 v[222:223], s[16:17], 0, v[132:133]
	s_mov_b32 m0, s35
	s_nop 0
	global_load_lds_dwordx4 v[222:223], off
	s_waitcnt vmcnt(8)
	s_waitcnt lgkmcnt(0)
	s_barrier
	v_mfma_f32_16x16x32_bf16 v[124:127], v[144:147], v[184:187], v[124:127]
	v_mfma_f32_16x16x32_bf16 v[120:123], v[160:163], v[184:187], v[120:123]
	v_mfma_f32_16x16x32_bf16 v[116:119], v[144:147], v[192:195], v[116:119]
	v_mfma_f32_16x16x32_bf16 v[112:115], v[160:163], v[192:195], v[112:115]
	v_mfma_f32_16x16x32_bf16 v[92:95], v[144:147], v[200:203], v[92:95]
	v_mfma_f32_16x16x32_bf16 v[88:91], v[160:163], v[200:203], v[88:91]
	v_mfma_f32_16x16x32_bf16 v[84:87], v[144:147], v[208:211], v[84:87]
	v_mfma_f32_16x16x32_bf16 v[80:83], v[160:163], v[208:211], v[80:83]
	v_mfma_f32_16x16x32_bf16 v[124:127], v[156:159], v[188:191], v[124:127]
	v_mfma_f32_16x16x32_bf16 v[120:123], v[164:167], v[188:191], v[120:123]
	v_mfma_f32_16x16x32_bf16 v[116:119], v[156:159], v[196:199], v[116:119]
	v_mfma_f32_16x16x32_bf16 v[112:115], v[164:167], v[196:199], v[112:115]
	v_mfma_f32_16x16x32_bf16 v[92:95], v[156:159], v[204:207], v[92:95]
	v_mfma_f32_16x16x32_bf16 v[88:91], v[164:167], v[204:207], v[88:91]
	v_mfma_f32_16x16x32_bf16 v[84:87], v[156:159], v[212:215], v[84:87]
	v_mfma_f32_16x16x32_bf16 v[80:83], v[164:167], v[212:215], v[80:83]
	v_mfma_f32_16x16x32_bf16 v[108:111], v[168:171], v[184:187], v[108:111]
	v_mfma_f32_16x16x32_bf16 v[104:107], v[176:179], v[184:187], v[104:107]
	v_mfma_f32_16x16x32_bf16 v[100:103], v[168:171], v[192:195], v[100:103]
	v_mfma_f32_16x16x32_bf16 v[96:99], v[176:179], v[192:195], v[96:99]
	v_mfma_f32_16x16x32_bf16 v[76:79], v[168:171], v[200:203], v[76:79]
	v_mfma_f32_16x16x32_bf16 v[72:75], v[176:179], v[200:203], v[72:75]
	v_mfma_f32_16x16x32_bf16 v[68:71], v[168:171], v[208:211], v[68:71]
	v_mfma_f32_16x16x32_bf16 v[64:67], v[176:179], v[208:211], v[64:67]
	v_mfma_f32_16x16x32_bf16 v[108:111], v[172:175], v[188:191], v[108:111]
	v_mfma_f32_16x16x32_bf16 v[104:107], v[180:183], v[188:191], v[104:107]
	v_mfma_f32_16x16x32_bf16 v[100:103], v[172:175], v[196:199], v[100:103]
	v_mfma_f32_16x16x32_bf16 v[96:99], v[180:183], v[196:199], v[96:99]
	v_mfma_f32_16x16x32_bf16 v[76:79], v[172:175], v[204:207], v[76:79]
	v_mfma_f32_16x16x32_bf16 v[72:75], v[180:183], v[204:207], v[72:75]
	v_mfma_f32_16x16x32_bf16 v[68:71], v[172:175], v[212:215], v[68:71]
	v_mfma_f32_16x16x32_bf16 v[64:67], v[180:183], v[212:215], v[64:67]
	s_barrier
; #define PG8_STAGE(bufoff, gbase, voff) do { _Pragma("unroll") for (int _i = 0; _i < 2; ++_i) \
;         __builtin_amdgcn_global_load_lds((const unsigned*)((const char*)(gbase) + (voff)[_i]), (PG8_LAS unsigned*)(lds + (bufoff) + ldsw + _i * 8192), 16, 0, 0); } while (0)
; #define PG8_LDA(dst, b, h) do { _Pragma("unroll") for (int m = 0; m < 4; ++m) _Pragma("unroll") for (int k = 0; k < 2; ++k) dst[m][k] = *(const PG8_LAS bf16x8*)(lds + PG8_SA(b, h) + aoff + m * 2048 + k * 1024); } while (0)
; #define PG8_MMA(ai, bj, At, Bt) do { __builtin_amdgcn_s_setprio(1); _Pragma("unroll") for (int m = 0; m < 4; ++m) _Pragma("unroll") for (int n = 0; n < 2; ++n) _Pragma("unroll") for (int k = 0; k < 2; ++k) \
;         acc[ai][bj][m][n] = __builtin_amdgcn_mfma_f32_16x16x32_bf16(Bt[n][k], At[m][k], acc[ai][bj][m][n], 0, 0, 0); __builtin_amdgcn_s_setprio(0); } while (0)
; #define PG8_WAIT_V(n) asm volatile("s_waitcnt vmcnt(" #n ")" ::: "memory")
; #define PG8_WAIT_L(n) asm volatile("s_waitcnt lgkmcnt(" #n ")" ::: "memory")
; #define PG8_BAR __builtin_amdgcn_s_barrier()
; #define PG8_SCHED __builtin_amdgcn_sched_barrier(0)
; template <class Epi, class Sched, bool ALIGN_EPI = false, bool SP2 = false>
; __device__ __forceinline__ void gemm_phase(PG8_LAS unsigned char* lds, const Gemm g, const Sched& S, const Epi& E, const int wv0) {
;     ...
;             PG8_LDA(At, 1, 1); PG8_STAGE(PG8_SB(1, 0), b3, voffB); PG8_STAGE(PG8_SB(1, 1), b3 + hstepB, voffB); PG8_STAGE(PG8_SA(1, 0), a3, voffA);
;             PG8_WAIT_V(8); PG8_WAIT_L(0); PG8_BAR; PG8_MMA(1, 0, At, B0); PG8_MMA(1, 1, At, B1); PG8_BAR; PG8_SCHED;
	ds_read_b128 v[184:187], v155 offset:49152
	ds_read_b128 v[188:191], v155 offset:50176
	ds_read_b128 v[192:195], v155 offset:51200
	ds_read_b128 v[196:199], v155 offset:52224
	ds_read_b128 v[200:203], v155 offset:53248
	ds_read_b128 v[204:207], v155 offset:54272
	ds_read_b128 v[208:211], v155 offset:55296
	ds_read_b128 v[212:215], v155 offset:56320
	s_add_i32 s16, s49, s29
	s_mov_b32 m0, s16
	v_lshl_add_u64 v[148:149], v[148:149], 0, s[8:9]
	global_load_lds_dwordx4 v[148:149], off
	s_add_i32 m0, s16, 0x2000
	s_add_u32 s16, s20, 0x160080
	v_lshl_add_u64 v[148:149], v[216:217], 0, s[8:9]
	s_addc_u32 s17, s21, 0
	s_add_i32 s20, s50, s29
	global_load_lds_dwordx4 v[148:149], off
	v_lshl_add_u64 v[148:149], s[16:17], 0, v[130:131]
	s_mov_b32 m0, s20
	s_nop 0
	global_load_lds_dwordx4 v[148:149], off
	v_lshl_add_u64 v[148:149], s[16:17], 0, v[134:135]
	s_add_i32 m0, s20, 0x2000
	s_nop 0
	global_load_lds_dwordx4 v[148:149], off
	v_lshl_add_u64 v[148:149], v[218:219], 0, s[8:9]
	s_mov_b32 m0, s37
	s_nop 0
	global_load_lds_dwordx4 v[148:149], off
	v_lshl_add_u64 v[148:149], v[220:221], 0, s[8:9]
	s_mov_b32 m0, s38
	s_nop 0
	global_load_lds_dwordx4 v[148:149], off
	s_waitcnt vmcnt(8)
	s_waitcnt lgkmcnt(0)
	s_barrier
	v_mfma_f32_16x16x32_bf16 v[60:63], v[144:147], v[184:187], v[60:63]
	v_mfma_f32_16x16x32_bf16 v[56:59], v[160:163], v[184:187], v[56:59]
	v_mfma_f32_16x16x32_bf16 v[52:55], v[144:147], v[192:195], v[52:55]
	v_mfma_f32_16x16x32_bf16 v[48:51], v[160:163], v[192:195], v[48:51]
	v_mfma_f32_16x16x32_bf16 v[28:31], v[144:147], v[200:203], v[28:31]
	v_mfma_f32_16x16x32_bf16 v[24:27], v[160:163], v[200:203], v[24:27]
	v_mfma_f32_16x16x32_bf16 v[20:23], v[144:147], v[208:211], v[20:23]
	v_mfma_f32_16x16x32_bf16 v[16:19], v[160:163], v[208:211], v[16:19]
	v_mfma_f32_16x16x32_bf16 v[60:63], v[156:159], v[188:191], v[60:63]
	v_mfma_f32_16x16x32_bf16 v[56:59], v[164:167], v[188:191], v[56:59]
	v_mfma_f32_16x16x32_bf16 v[52:55], v[156:159], v[196:199], v[52:55]
	v_mfma_f32_16x16x32_bf16 v[48:51], v[164:167], v[196:199], v[48:51]
	v_mfma_f32_16x16x32_bf16 v[28:31], v[156:159], v[204:207], v[28:31]
	v_mfma_f32_16x16x32_bf16 v[24:27], v[164:167], v[204:207], v[24:27]
	v_mfma_f32_16x16x32_bf16 v[20:23], v[156:159], v[212:215], v[20:23]
	v_mfma_f32_16x16x32_bf16 v[16:19], v[164:167], v[212:215], v[16:19]
	v_mfma_f32_16x16x32_bf16 v[44:47], v[168:171], v[184:187], v[44:47]
	v_mfma_f32_16x16x32_bf16 v[40:43], v[176:179], v[184:187], v[40:43]
	v_mfma_f32_16x16x32_bf16 v[36:39], v[168:171], v[192:195], v[36:39]
	v_mfma_f32_16x16x32_bf16 v[32:35], v[176:179], v[192:195], v[32:35]
	v_mfma_f32_16x16x32_bf16 v[12:15], v[168:171], v[200:203], v[12:15]
	v_mfma_f32_16x16x32_bf16 v[8:11], v[176:179], v[200:203], v[8:11]
	v_mfma_f32_16x16x32_bf16 v[4:7], v[168:171], v[208:211], v[4:7]
	v_mfma_f32_16x16x32_bf16 v[0:3], v[176:179], v[208:211], v[0:3]
	v_mfma_f32_16x16x32_bf16 v[44:47], v[172:175], v[188:191], v[44:47]
	v_mfma_f32_16x16x32_bf16 v[40:43], v[180:183], v[188:191], v[40:43]
	v_mfma_f32_16x16x32_bf16 v[36:39], v[172:175], v[196:199], v[36:39]
	v_mfma_f32_16x16x32_bf16 v[32:35], v[180:183], v[196:199], v[32:35]
	v_mfma_f32_16x16x32_bf16 v[12:15], v[172:175], v[204:207], v[12:15]
	v_mfma_f32_16x16x32_bf16 v[8:11], v[180:183], v[204:207], v[8:11]
	v_mfma_f32_16x16x32_bf16 v[4:7], v[172:175], v[212:215], v[4:7]
	v_mfma_f32_16x16x32_bf16 v[0:3], v[180:183], v[212:215], v[0:3]
	s_barrier
	s_add_i32 s48, s48, 2
	s_add_u32 s46, s46, 0x100
	s_addc_u32 s47, s47, 0
	s_cmpk_gt_u32 s48, 0x55
	s_mov_b64 s[16:17], s[18:19]
	s_cbranch_scc0 .LBB0_1808
	s_and_b64 vcc, exec, s[10:11]
	s_cbranch_vccz .LBB0_1811
	s_barrier
